# context-row work of mlp1 / out-projection / mlp2 (layer 0) folded into the hand-written GEMM phases; grid barrier between the independent S3a and S3b phases skipped
# speedup vs baseline: 1.2513x; 1.0156x over previous
; #define FOR_ITEMS(N) for (int item = blockIdx.x; item < (N); item += gridDim.x)
; __device__ __forceinline__ void xcd_barrier(const XcdBarrier& b) {
;   asm volatile("s_waitcnt vmcnt(0)" ::: "memory");
;   __syncthreads();
;   if (threadIdx.x == 0) {
;     unsigned* bar = b.bar;
;     __builtin_amdgcn_s_waitcnt(0);
;     unsigned nloc = b.st[0], nx = b.st[1];
;     if (nloc == 0u) { xcd_barrier_complete(bar, b.x, nloc, nx); b.st[0] = nloc; b.st[1] = nx; }
; __global__ void __launch_bounds__(256, 2) fwd_megakernel(Params p_unused) {
;     ...
;         FOR_ITEMS(16 + 32 + 1056) {
;           if (item < 16) phase_s5_carry(p, l, item);
;           else if (item < 48) phase_fnet2(p, item - 16 + 1024, smem);
;           else phase_conv(p, l, item - 48, smem);
;         }
;       }
;       xcd_barrier(xb);
;       { CParams& p = kparams(); FOR_ITEMS(512) phase_fn_step2(p, item, smem); }
;       xcd_barrier(xb);
.LBB0_577:
	s_waitcnt vmcnt(0)
	v_readlane_b32 s28, v225, 2
	s_mov_b32 s20, s18
	s_movk_i32 s0, 0x4000
	v_readlane_b32 s29, v225, 3
	s_barrier
	s_and_saveexec_b64 s[22:23], s[28:29]
	v_readlane_b32 s34, v224, 20
	v_readlane_b32 s38, v224, 22
	v_readlane_b32 s52, v224, 24
	v_readlane_b32 s10, v225, 4
	v_readlane_b32 s35, v224, 21
	v_readlane_b32 s39, v224, 23
	v_readlane_b32 s53, v224, 25
	s_branch .LBB0_629
	s_waitcnt vmcnt(0) expcnt(0) lgkmcnt(0)
	ds_read_b32 v2, v145 offset:40960
	ds_read_b32 v0, v145 offset:40964
	s_waitcnt lgkmcnt(1)
	v_cmp_ne_u32_e32 vcc, 0, v2
	s_cbranch_vccnz .LBB0_593
	s_mov_b32 s2, 1
	s_branch .LBB0_581

; __device__ __forceinline__ int otid() { int t = threadIdx.x; asm volatile("" : "+v"(t)); return t; }
; __device__ void phase_proj_res(CParams& p, int l, int tm, int tn, char* smem, const bf16_t* A, int K,
;                                const bf16_t* Bt, int gate_off, float gscale) {
;     ...
;   int row0 = tm * 128, col0 = tn * 128;
;   f32x4 acc[4][4];
;   zero_acc<4>(acc);
;   gemm_mainloop<4>(A + (size_t)row0 * K, K, Bt + (size_t)col0 * K, K, K, sA, sB, acc, tid);
;   const float* md = p.mod + ((size_t)l * 3 + modvec_of_tok(row0)) * 6144 + gate_off;
;   EPI_LOOP({
;     float* xp = xrow(p, row0 + rl) + col0 + cl;
;     *xp = *xp + gscale * md[col0 + cl] * acc[mi][ni][j];
;   })
; }
; __device__ void phase_proj_res_ctx(CParams& p, int l, int item, char* smem, const bf16_t* A, int K,
;                                    const bf16_t* Bt, int gate_off) {
;   const int tid = otid();
;   bf16_t* sA = (bf16_t*)smem;
;   bf16_t* sB = sA + 128 * LDSS;
;   int ks = item & 3, tn = (item >> 2) & 7, tmc = item >> 5;
;   int row0 = NLAT + tmc * 128, col0 = tn * 128;
;   int kc = K >> 2;
;   f32x4 acc[4][4];
;   zero_acc<4>(acc);
;   gemm_mainloop<4>(A + (size_t)row0 * K + ks * kc, K, Bt + (size_t)col0 * K + ks * kc, K, kc, sA, sB, acc, tid);
.LBB0_946:
	s_or_b64 exec, exec, s[22:23]
	s_mov_b64 s[42:43], s[34:35]
	s_waitcnt lgkmcnt(0)
	s_barrier
	s_lshl_b64 s[6:7], s[0:1], 21
	s_load_dwordx2 s[8:9], s[42:43], 0x118
	s_load_dwordx2 s[22:23], s[42:43], 0x1d8
	s_load_dwordx2 s[24:25], s[42:43], 0x160
	s_load_dwordx2 s[44:45], s[42:43], 0x148
	s_load_dwordx2 s[48:49], s[42:43], 0xf8
	s_waitcnt lgkmcnt(0)
	s_add_u32 s2, s8, s6
	s_addc_u32 s4, s9, s7
	v_readlane_b32 s6, v225, 63
	v_readlane_b32 s7, v224, 0
	s_add_u32 s50, s2, s6
	s_addc_u32 s51, s4, s7
	s_mov_b32 s2, 0
	s_mov_b64 exec, -1
	ds_read_b128 v[252:255], v145 offset:40960
	s_load_dwordx2 s[0:1], s[34:35], 0x1d8
	s_load_dwordx2 s[6:7], s[34:35], 0x118
	s_load_dwordx2 s[24:25], s[34:35], 0xf8
	s_load_dwordx2 s[28:29], s[34:35], 0x160
	v_readlane_b32 s2, v224, 26
	v_readlane_b32 s4, v225, 4
	v_readfirstlane_b32 s53, v147
	v_and_b32_e32 v166, 63, v147
	s_nop 3
	s_lshr_b32 s53, s53, 6
	s_lshl_b32 s32, s53, 12
	v_lshrrev_b32_e32 v167, 3, v166
	s_lshl_b32 s57, s53, 5
	v_add_u32_e32 v167, s57, v167
	v_and_b32_e32 v226, 7, v166
	v_lshrrev_b32_e32 v227, 4, v166
	s_mov_b32 s55, 0x800
	s_mov_b32 s56, 0x800
	v_xor_b32_e32 v248, v226, v227
	v_xor_b32_e32 v249, 0, v248
	v_lshlrev_b32_e32 v249, 4, v249
	v_add_u32_e32 v250, 0, v167
	v_mul_lo_u32 v236, v250, s55
	v_add_u32_e32 v236, v236, v249
	v_mul_lo_u32 v240, v250, s56
	v_add_u32_e32 v240, v240, v249
	v_xor_b32_e32 v249, 4, v248
	v_lshlrev_b32_e32 v249, 4, v249
	v_add_u32_e32 v250, 8, v167
	v_mul_lo_u32 v237, v250, s55
	v_add_u32_e32 v237, v237, v249
	v_mul_lo_u32 v241, v250, s56
	v_add_u32_e32 v241, v241, v249
	v_xor_b32_e32 v249, 0, v248
	v_lshlrev_b32_e32 v249, 4, v249
	v_add_u32_e32 v250, 16, v167
	v_mul_lo_u32 v238, v250, s55
	v_add_u32_e32 v238, v238, v249
	v_mul_lo_u32 v242, v250, s56
	v_add_u32_e32 v242, v242, v249
	v_xor_b32_e32 v249, 4, v248
	v_lshlrev_b32_e32 v249, 4, v249
	v_add_u32_e32 v250, 24, v167
	v_mul_lo_u32 v239, v250, s55
	v_add_u32_e32 v239, v239, v249
	v_mul_lo_u32 v243, v250, s56
	v_add_u32_e32 v243, v243, v249
	v_and_b32_e32 v167, 15, v166
	v_lshrrev_b32_e32 v227, 4, v166
	s_lshr_b32 s57, s53, 1
	s_and_b32 s58, s53, 1
	s_lshl_b32 s57, s57, 6
	s_lshl_b32 s58, s58, 6
	v_lshrrev_b32_e32 v226, 1, v167
	v_xor_b32_e32 v226, v227, v226
	v_lshlrev_b32_e32 v226, 4, v226
	v_add_u32_e32 v248, s57, v167
	v_lshl_add_u32 v248, v248, 7, v226
	v_xor_b32_e32 v249, 64, v248
	v_add_u32_e32 v250, s58, v167
	v_lshl_add_u32 v250, v250, 7, v226
	v_xor_b32_e32 v251, 64, v250
	v_lshl_add_u32 v132, v227, 2, s58
	v_lshlrev_b32_e32 v132, 2, v132
	v_add_u32_e32 v144, s57, v167
	v_lshl_add_u32 v144, v144, 12, v132
	s_mov_b32 s59, 0x0
	s_mov_b32 s62, 0x4000
	s_mov_b32 s63, 0x8000
	s_mov_b32 s92, 0xc000
	s_mov_b32 s93, 0x10000
	s_waitcnt lgkmcnt(0)
	s_mov_b32 s52, 0
	s_and_b32 s55, s4, 7
	s_lshl_b32 s55, s55, 4
	s_lshr_b32 s56, s4, 5
	s_add_u32 s55, s55, s56
	s_lshl_b32 s50, s55, 7
	s_lshr_b32 s56, s4, 3
	s_and_b32 s56, s56, 3
	s_lshl_b32 s56, s56, 1
	s_add_u32 s56, s56, s52
	s_lshl_b32 s51, s56, 7
	s_lshr_b32 s55, s4, 5
	s_lshl_b32 s55, s55, 7
	s_add_u32 s55, s55, 0x4000
	s_lshr_b32 s56, s4, 2
	s_and_b32 s56, s56, 7
	s_lshl_b32 s56, s56, 7
	s_and_b32 s57, s4, 3
	s_mul_i32 s57, s57, 0x200
	s_cmp_ge_u32 s52, 2
	s_cselect_b32 s50, s55, s50
	s_cselect_b32 s51, s56, s51
	s_cselect_b32 s57, s57, 0
	s_mul_i32 s55, s50, 0x800
	s_add_u32 s55, s55, s57
	s_add_u32 s8, s0, s55
	s_addc_u32 s9, s1, 0
	s_mul_i32 s55, s2, 0x200000
	s_mul_i32 s56, s51, 0x800
	s_add_u32 s55, s55, s56
	s_add_u32 s55, s55, s57
	s_add_u32 s12, s6, s55
	s_addc_u32 s13, s7, 0
	s_barrier
	s_add_u32 s54, s32, s59
	s_add_u32 m0, s54, 0x0
	s_nop 0
	global_load_lds_dwordx4 v236, s[8:9]
	s_add_u32 m0, s54, 0x400
	s_nop 0
	global_load_lds_dwordx4 v237, s[8:9]
	s_add_u32 m0, s54, 0x800
	s_nop 0
	global_load_lds_dwordx4 v238, s[8:9]
	s_add_u32 m0, s54, 0xc00
	s_nop 0
	global_load_lds_dwordx4 v239, s[8:9]
	s_add_u32 s8, s8, 128
	s_addc_u32 s9, s9, 0
	s_add_u32 s54, s32, s62
	s_add_u32 m0, s54, 0x0
	s_nop 0
	global_load_lds_dwordx4 v240, s[12:13]
	s_add_u32 m0, s54, 0x400
	s_nop 0
	global_load_lds_dwordx4 v241, s[12:13]
	s_add_u32 m0, s54, 0x800
	s_nop 0
	global_load_lds_dwordx4 v242, s[12:13]
	s_add_u32 m0, s54, 0xc00
	s_nop 0
	global_load_lds_dwordx4 v243, s[12:13]
	s_add_u32 s12, s12, 128
	s_addc_u32 s13, s13, 0
	s_add_u32 s54, s32, s63
	s_add_u32 m0, s54, 0x0
	s_nop 0
	global_load_lds_dwordx4 v236, s[8:9]
	s_add_u32 m0, s54, 0x400
	s_nop 0
	global_load_lds_dwordx4 v237, s[8:9]
	s_add_u32 m0, s54, 0x800
	s_nop 0
	global_load_lds_dwordx4 v238, s[8:9]
	s_add_u32 m0, s54, 0xc00
	s_nop 0
	global_load_lds_dwordx4 v239, s[8:9]
	s_add_u32 s8, s8, 128
	s_addc_u32 s9, s9, 0
	s_add_u32 s54, s32, s92
	s_add_u32 m0, s54, 0x0
	s_nop 0
	global_load_lds_dwordx4 v240, s[12:13]
	s_add_u32 m0, s54, 0x400
	s_nop 0
	global_load_lds_dwordx4 v241, s[12:13]
	s_add_u32 m0, s54, 0x800
	s_nop 0
	global_load_lds_dwordx4 v242, s[12:13]
	s_add_u32 m0, s54, 0xc00
	s_nop 0
	global_load_lds_dwordx4 v243, s[12:13]
	s_add_u32 s12, s12, 128
	s_addc_u32 s13, s13, 0
	v_mov_b32_e32 v0, 0
	v_mov_b32_e32 v1, 0
	v_mov_b32_e32 v2, 0
	v_mov_b32_e32 v3, 0
	v_mov_b32_e32 v4, 0
	v_mov_b32_e32 v5, 0
	v_mov_b32_e32 v6, 0
	v_mov_b32_e32 v7, 0
	v_mov_b32_e32 v8, 0
	v_mov_b32_e32 v9, 0
	v_mov_b32_e32 v10, 0
	v_mov_b32_e32 v11, 0
	v_mov_b32_e32 v12, 0
	v_mov_b32_e32 v13, 0
	v_mov_b32_e32 v14, 0
	v_mov_b32_e32 v15, 0
	v_mov_b32_e32 v16, 0
	v_mov_b32_e32 v17, 0
	v_mov_b32_e32 v18, 0
	v_mov_b32_e32 v19, 0
	v_mov_b32_e32 v20, 0
	v_mov_b32_e32 v21, 0
	v_mov_b32_e32 v22, 0
	v_mov_b32_e32 v23, 0
	v_mov_b32_e32 v24, 0
	v_mov_b32_e32 v25, 0
	v_mov_b32_e32 v26, 0
	v_mov_b32_e32 v27, 0
	v_mov_b32_e32 v28, 0
	v_mov_b32_e32 v29, 0
	v_mov_b32_e32 v30, 0
	v_mov_b32_e32 v31, 0
	v_mov_b32_e32 v32, 0
	v_mov_b32_e32 v33, 0
	v_mov_b32_e32 v34, 0
	v_mov_b32_e32 v35, 0
	v_mov_b32_e32 v36, 0
	v_mov_b32_e32 v37, 0
	v_mov_b32_e32 v38, 0
	v_mov_b32_e32 v39, 0
	v_mov_b32_e32 v40, 0
	v_mov_b32_e32 v41, 0
	v_mov_b32_e32 v42, 0
	v_mov_b32_e32 v43, 0
	v_mov_b32_e32 v44, 0
	v_mov_b32_e32 v45, 0
	v_mov_b32_e32 v46, 0
	v_mov_b32_e32 v47, 0
	v_mov_b32_e32 v48, 0
	v_mov_b32_e32 v49, 0
	v_mov_b32_e32 v50, 0
	v_mov_b32_e32 v51, 0
	v_mov_b32_e32 v52, 0
	v_mov_b32_e32 v53, 0
	v_mov_b32_e32 v54, 0
	v_mov_b32_e32 v55, 0
	v_mov_b32_e32 v56, 0
	v_mov_b32_e32 v57, 0
	v_mov_b32_e32 v58, 0
	v_mov_b32_e32 v59, 0
	v_mov_b32_e32 v60, 0
	v_mov_b32_e32 v61, 0
	v_mov_b32_e32 v62, 0
	v_mov_b32_e32 v63, 0
	s_waitcnt vmcnt(8)
	s_barrier
	v_add_u32_e32 v128, s59, v248
	v_add_u32_e32 v130, s62, v250
	ds_read_b128 v[168:171], v128 offset:0
	ds_read_b128 v[184:187], v130 offset:0
	ds_read_b128 v[172:175], v128 offset:2048
	ds_read_b128 v[188:191], v130 offset:2048
	ds_read_b128 v[176:179], v128 offset:4096
	ds_read_b128 v[192:195], v130 offset:4096
	ds_read_b128 v[180:183], v128 offset:6144
	ds_read_b128 v[196:199], v130 offset:6144
; __device__ __forceinline__ int otid() { int t = threadIdx.x; asm volatile("" : "+v"(t)); return t; }
; #define FOR_TILES(TM, TN, SR, SC) for (int r_ = 0, nr_ = swz_rounds(TM, TN, SR, SC); r_ < nr_; r_++) if (int tm = 0, tn = 0; swz_tile(r_, TM, TN, SR, SC, tm, tn))
; #define FOR_ITEMS(N) for (int item = blockIdx.x; item < (N); item += gridDim.x)
; #define REPS(k) for (int rep = 0; rep < ((PROBE_DUP == (k)) ? 2 : 1); rep++)
; __device__ void phase_proj_res_ctx(CParams& p, int l, int item, char* smem, const bf16_t* A, int K,
;                                    const bf16_t* Bt, int gate_off) {
;   const int tid = otid();
;   bf16_t* sA = (bf16_t*)smem;
;   bf16_t* sB = sA + 128 * LDSS;
;   int ks = item & 3, tn = (item >> 2) & 7, tmc = item >> 5;
;   int row0 = NLAT + tmc * 128, col0 = tn * 128;
;   int kc = K >> 2;
;   f32x4 acc[4][4];
;   zero_acc<4>(acc);
;   gemm_mainloop<4>(A + (size_t)row0 * K + ks * kc, K, Bt + (size_t)col0 * K + ks * kc, K, kc, sA, sB, acc, tid);
;   const float* md = p.mod + ((size_t)l * 3 + 2) * 6144 + gate_off;
;   float* part = (float*)p.YT1 + (size_t)ks * 512 * DM;
;   EPI_LOOP({ part[(size_t)(row0 - NLAT + rl) * DM + col0 + cl] = md[col0 + cl] * acc[mi][ni][j]; })
; }
; __global__ void __launch_bounds__(256, 2) fwd_megakernel(Params p_unused) {
;     ...
;     REPS(1) {
;       { CParams& p = kparams();
;         FOR_TILES(128, 8, 8, 8) phase_proj_res(p, l, tm, tn, smem, p.merged, 1024, p.WoT + (size_t)l * DM * DM, 2048, rep == 0 ? 1.f : 0.f);
;         if (l == 0 && rep == 0) { FOR_ITEMS(128) phase_proj_res_ctx(p, l, item, smem, p.merged, 1024, p.WoT + (size_t)l * DM * DM, 2048); } }
;       xcd_barrier(xb);
.Loutp_tile:
	s_mul_i32 s55, s2, 3
	s_lshr_b32 s56, s50, 13
	s_add_u32 s55, s55, s56
	s_mul_i32 s55, s55, 6144
	s_add_u32 s55, s55, s51
	s_add_u32 s55, s55, 2048
	s_lshl_b32 s55, s55, 2
	s_add_u32 s44, s28, s55
	s_addc_u32 s45, s29, 0
	s_lshl_b32 s55, s50, 12
	s_lshl_b32 s56, s51, 2
	s_add_u32 s55, s55, s56
	s_add_u32 s26, s24, s55
	s_addc_u32 s27, s25, 0
	s_cmp_ge_u32 s52, 2
	s_cselect_b32 s98, 4, 16
	s_cbranch_scc0 .Loutp_xtdone
	s_load_dwordx2 s[26:27], s[34:35], 0x200
	s_sub_u32 s55, s50, 0x4000
	s_lshl_b32 s55, s55, 12
	s_lshl_b32 s56, s51, 2
	s_add_u32 s55, s55, s56
	s_and_b32 s56, s4, 3
	s_lshl_b32 s56, s56, 21
	s_add_u32 s55, s55, s56
	s_waitcnt lgkmcnt(0)
	s_add_u32 s26, s26, s55
	s_addc_u32 s27, s27, 0
.Loutp_xtdone:
	s_add_u32 s58, s52, 1
	s_cmp_lt_u32 s4, 128
	s_cselect_b32 s57, 1, 0
	s_cmp_eq_u32 s2, 0
	s_cselect_b32 s57, s57, 0
	s_add_u32 s57, s57, 1
	s_min_u32 s58, s58, s57
	s_and_b32 s55, s4, 7
	s_lshl_b32 s55, s55, 4
	s_lshr_b32 s56, s4, 5
	s_add_u32 s55, s55, s56
	s_lshl_b32 s50, s55, 7
	s_lshr_b32 s56, s4, 3
	s_and_b32 s56, s56, 3
	s_lshl_b32 s56, s56, 1
	s_add_u32 s56, s56, s58
	s_lshl_b32 s51, s56, 7
	s_lshr_b32 s55, s4, 5
	s_lshl_b32 s55, s55, 7
	s_add_u32 s55, s55, 0x4000
	s_lshr_b32 s56, s4, 2
	s_and_b32 s56, s56, 7
	s_lshl_b32 s56, s56, 7
	s_and_b32 s57, s4, 3
	s_mul_i32 s57, s57, 0x200
	s_cmp_ge_u32 s58, 2
	s_cselect_b32 s50, s55, s50
	s_cselect_b32 s51, s56, s51
	s_cselect_b32 s57, s57, 0
	s_mul_i32 s55, s50, 0x800
	s_add_u32 s55, s55, s57
	s_add_u32 s18, s0, s55
	s_addc_u32 s19, s1, 0
	s_mul_i32 s55, s2, 0x200000
	s_mul_i32 s56, s51, 0x800
	s_add_u32 s55, s55, s56
	s_add_u32 s55, s55, s57
	s_add_u32 s22, s6, s55
	s_addc_u32 s23, s7, 0
	s_mov_b32 s53, 0
.Loutp_pair:
	s_add_u32 s55, s53, 2
	s_cmp_eq_u32 s55, s98
	s_cselect_b64 s[8:9], s[18:19], s[8:9]
	s_add_u32 s54, s32, s93
	s_add_u32 m0, s54, 0x0
	s_nop 0
	global_load_lds_dwordx4 v236, s[8:9]
	s_add_u32 m0, s54, 0x400
	s_nop 0
	global_load_lds_dwordx4 v237, s[8:9]
	s_add_u32 m0, s54, 0x800
	s_nop 0
	global_load_lds_dwordx4 v238, s[8:9]
	s_add_u32 m0, s54, 0xc00
	s_nop 0
	global_load_lds_dwordx4 v239, s[8:9]
	s_add_u32 s8, s8, 128
	s_addc_u32 s9, s9, 0
	v_add_u32_e32 v129, s59, v249
	v_add_u32_e32 v131, s62, v251
	s_waitcnt lgkmcnt(0)
	v_mfma_f32_16x16x32_bf16 v[0:3], v[184:187], v[168:171], v[0:3]
	ds_read_b128 v[200:203], v129 offset:0
	v_mfma_f32_16x16x32_bf16 v[4:7], v[188:191], v[168:171], v[4:7]
	ds_read_b128 v[216:219], v131 offset:0
	v_mfma_f32_16x16x32_bf16 v[8:11], v[192:195], v[168:171], v[8:11]
	ds_read_b128 v[204:207], v129 offset:2048
	v_mfma_f32_16x16x32_bf16 v[12:15], v[196:199], v[168:171], v[12:15]
	ds_read_b128 v[220:223], v131 offset:2048
	v_mfma_f32_16x16x32_bf16 v[16:19], v[184:187], v[172:175], v[16:19]
	ds_read_b128 v[208:211], v129 offset:4096
	v_mfma_f32_16x16x32_bf16 v[20:23], v[188:191], v[172:175], v[20:23]
	ds_read_b128 v[228:231], v131 offset:4096
	v_mfma_f32_16x16x32_bf16 v[24:27], v[192:195], v[172:175], v[24:27]
	ds_read_b128 v[212:215], v129 offset:6144
	v_mfma_f32_16x16x32_bf16 v[28:31], v[196:199], v[172:175], v[28:31]
	ds_read_b128 v[232:235], v131 offset:6144
	v_mfma_f32_16x16x32_bf16 v[32:35], v[184:187], v[176:179], v[32:35]
	v_mfma_f32_16x16x32_bf16 v[36:39], v[188:191], v[176:179], v[36:39]
	v_mfma_f32_16x16x32_bf16 v[40:43], v[192:195], v[176:179], v[40:43]
	v_mfma_f32_16x16x32_bf16 v[44:47], v[196:199], v[176:179], v[44:47]
	v_mfma_f32_16x16x32_bf16 v[48:51], v[184:187], v[180:183], v[48:51]
	v_mfma_f32_16x16x32_bf16 v[52:55], v[188:191], v[180:183], v[52:55]
	v_mfma_f32_16x16x32_bf16 v[56:59], v[192:195], v[180:183], v[56:59]
	v_mfma_f32_16x16x32_bf16 v[60:63], v[196:199], v[180:183], v[60:63]
	s_waitcnt vmcnt(4) lgkmcnt(0)
	s_barrier
	s_add_u32 s55, s53, 2
	s_cmp_eq_u32 s55, s98
	s_cselect_b64 s[12:13], s[22:23], s[12:13]
	s_add_u32 s54, s32, s59
	s_add_u32 m0, s54, 0x0
	s_nop 0
	global_load_lds_dwordx4 v240, s[12:13]
	s_add_u32 m0, s54, 0x400
	s_nop 0
	global_load_lds_dwordx4 v241, s[12:13]
	s_add_u32 m0, s54, 0x800
	s_nop 0
	global_load_lds_dwordx4 v242, s[12:13]
	s_add_u32 m0, s54, 0xc00
	s_nop 0
	global_load_lds_dwordx4 v243, s[12:13]
	s_add_u32 s12, s12, 128
	s_addc_u32 s13, s13, 0
	v_add_u32_e32 v128, s63, v248
	v_add_u32_e32 v130, s92, v250
	v_mfma_f32_16x16x32_bf16 v[0:3], v[216:219], v[200:203], v[0:3]
	ds_read_b128 v[168:171], v128 offset:0
	v_mfma_f32_16x16x32_bf16 v[4:7], v[220:223], v[200:203], v[4:7]
	ds_read_b128 v[184:187], v130 offset:0
	v_mfma_f32_16x16x32_bf16 v[8:11], v[228:231], v[200:203], v[8:11]
	ds_read_b128 v[172:175], v128 offset:2048
	v_mfma_f32_16x16x32_bf16 v[12:15], v[232:235], v[200:203], v[12:15]
	ds_read_b128 v[188:191], v130 offset:2048
	v_mfma_f32_16x16x32_bf16 v[16:19], v[216:219], v[204:207], v[16:19]
	ds_read_b128 v[176:179], v128 offset:4096
	v_mfma_f32_16x16x32_bf16 v[20:23], v[220:223], v[204:207], v[20:23]
	ds_read_b128 v[192:195], v130 offset:4096
	v_mfma_f32_16x16x32_bf16 v[24:27], v[228:231], v[204:207], v[24:27]
	ds_read_b128 v[180:183], v128 offset:6144
	v_mfma_f32_16x16x32_bf16 v[28:31], v[232:235], v[204:207], v[28:31]
	ds_read_b128 v[196:199], v130 offset:6144
	v_mfma_f32_16x16x32_bf16 v[32:35], v[216:219], v[208:211], v[32:35]
	v_mfma_f32_16x16x32_bf16 v[36:39], v[220:223], v[208:211], v[36:39]
	v_mfma_f32_16x16x32_bf16 v[40:43], v[228:231], v[208:211], v[40:43]
	v_mfma_f32_16x16x32_bf16 v[44:47], v[232:235], v[208:211], v[44:47]
	v_mfma_f32_16x16x32_bf16 v[48:51], v[216:219], v[212:215], v[48:51]
	v_mfma_f32_16x16x32_bf16 v[52:55], v[220:223], v[212:215], v[52:55]
	v_mfma_f32_16x16x32_bf16 v[56:59], v[228:231], v[212:215], v[56:59]
	v_mfma_f32_16x16x32_bf16 v[60:63], v[232:235], v[212:215], v[60:63]
	s_mov_b32 s55, s59
	s_mov_b32 s56, s62
	s_mov_b32 s59, s63
	s_mov_b32 s62, s92
	s_mov_b32 s63, s93
	s_mov_b32 s92, s55
	s_mov_b32 s93, s56
	s_add_u32 s53, s53, 1
	s_cmp_lt_u32 s53, s98
	s_cbranch_scc1 .Loutp_pair
; __device__ void phase_proj_res_ctx(CParams& p, int l, int item, char* smem, const bf16_t* A, int K,
;                                    const bf16_t* Bt, int gate_off) {
;     ...
;   const float* md = p.mod + ((size_t)l * 3 + 2) * 6144 + gate_off;
;   float* part = (float*)p.YT1 + (size_t)ks * 512 * DM;
;   EPI_LOOP({ part[(size_t)(row0 - NLAT + rl) * DM + col0 + cl] = md[col0 + cl] * acc[mi][ni][j]; })
	s_nop 15
	s_nop 7
	global_load_dwordx4 v[200:203], v132, s[44:45] offset:0
	global_load_dwordx4 v[204:207], v132, s[44:45] offset:64
	global_load_dwordx4 v[208:211], v132, s[44:45] offset:128
	global_load_dwordx4 v[212:215], v132, s[44:45] offset:192
	s_cmp_ge_u32 s52, 2
	s_cbranch_scc0 .Loutp_erw
	s_waitcnt vmcnt(0)
	v_mul_f32_e32 v64, v200, v0
	v_mul_f32_e32 v65, v201, v1
	v_mul_f32_e32 v66, v202, v2
	v_mul_f32_e32 v67, v203, v3
	v_mul_f32_e32 v68, v204, v4
	v_mul_f32_e32 v69, v205, v5
	v_mul_f32_e32 v70, v206, v6
	v_mul_f32_e32 v71, v207, v7
	v_mul_f32_e32 v72, v208, v8
	v_mul_f32_e32 v73, v209, v9
	v_mul_f32_e32 v74, v210, v10
	v_mul_f32_e32 v75, v211, v11
	v_mul_f32_e32 v76, v212, v12
	v_mul_f32_e32 v77, v213, v13
	v_mul_f32_e32 v78, v214, v14
	v_mul_f32_e32 v79, v215, v15
	global_store_dwordx4 v144, v[64:67], s[26:27] offset:0
	global_store_dwordx4 v144, v[68:71], s[26:27] offset:64
	global_store_dwordx4 v144, v[72:75], s[26:27] offset:128
	global_store_dwordx4 v144, v[76:79], s[26:27] offset:192
	s_add_u32 s26, s26, 0x10000
	s_addc_u32 s27, s27, 0
	v_mul_f32_e32 v80, v200, v16
	v_mul_f32_e32 v81, v201, v17
	v_mul_f32_e32 v82, v202, v18
	v_mul_f32_e32 v83, v203, v19
	v_mul_f32_e32 v84, v204, v20
	v_mul_f32_e32 v85, v205, v21
	v_mul_f32_e32 v86, v206, v22
	v_mul_f32_e32 v87, v207, v23
	v_mul_f32_e32 v88, v208, v24
	v_mul_f32_e32 v89, v209, v25
	v_mul_f32_e32 v90, v210, v26
	v_mul_f32_e32 v91, v211, v27
	v_mul_f32_e32 v92, v212, v28
	v_mul_f32_e32 v93, v213, v29
	v_mul_f32_e32 v94, v214, v30
	v_mul_f32_e32 v95, v215, v31
	global_store_dwordx4 v144, v[80:83], s[26:27] offset:0
	global_store_dwordx4 v144, v[84:87], s[26:27] offset:64
	global_store_dwordx4 v144, v[88:91], s[26:27] offset:128
	global_store_dwordx4 v144, v[92:95], s[26:27] offset:192
	s_add_u32 s26, s26, 0x10000
	s_addc_u32 s27, s27, 0
	v_mul_f32_e32 v96, v200, v32
	v_mul_f32_e32 v97, v201, v33
	v_mul_f32_e32 v98, v202, v34
	v_mul_f32_e32 v99, v203, v35
	v_mul_f32_e32 v100, v204, v36
	v_mul_f32_e32 v101, v205, v37
	v_mul_f32_e32 v102, v206, v38
	v_mul_f32_e32 v103, v207, v39
	v_mul_f32_e32 v104, v208, v40
	v_mul_f32_e32 v105, v209, v41
	v_mul_f32_e32 v106, v210, v42
	v_mul_f32_e32 v107, v211, v43
	v_mul_f32_e32 v108, v212, v44
	v_mul_f32_e32 v109, v213, v45
	v_mul_f32_e32 v110, v214, v46
	v_mul_f32_e32 v111, v215, v47
	global_store_dwordx4 v144, v[96:99], s[26:27] offset:0
	global_store_dwordx4 v144, v[100:103], s[26:27] offset:64
	global_store_dwordx4 v144, v[104:107], s[26:27] offset:128
	global_store_dwordx4 v144, v[108:111], s[26:27] offset:192
	s_add_u32 s26, s26, 0x10000
	s_addc_u32 s27, s27, 0
	v_mul_f32_e32 v112, v200, v48
	v_mul_f32_e32 v113, v201, v49
	v_mul_f32_e32 v114, v202, v50
	v_mul_f32_e32 v115, v203, v51
	v_mul_f32_e32 v116, v204, v52
	v_mul_f32_e32 v117, v205, v53
	v_mul_f32_e32 v118, v206, v54
	v_mul_f32_e32 v119, v207, v55
	v_mul_f32_e32 v120, v208, v56
	v_mul_f32_e32 v121, v209, v57
	v_mul_f32_e32 v122, v210, v58
	v_mul_f32_e32 v123, v211, v59
	v_mul_f32_e32 v124, v212, v60
	v_mul_f32_e32 v125, v213, v61
	v_mul_f32_e32 v126, v214, v62
	v_mul_f32_e32 v127, v215, v63
	global_store_dwordx4 v144, v[112:115], s[26:27] offset:0
	global_store_dwordx4 v144, v[116:119], s[26:27] offset:64
	global_store_dwordx4 v144, v[120:123], s[26:27] offset:128
	global_store_dwordx4 v144, v[124:127], s[26:27] offset:192
	s_branch .Loutp_edone
; #define FOR_TILES(TM, TN, SR, SC) for (int r_ = 0, nr_ = swz_rounds(TM, TN, SR, SC); r_ < nr_; r_++) if (int tm = 0, tn = 0; swz_tile(r_, TM, TN, SR, SC, tm, tn))
; #define FOR_ITEMS(N) for (int item = blockIdx.x; item < (N); item += gridDim.x)
; __device__ void phase_proj_res(CParams& p, int l, int tm, int tn, char* smem, const bf16_t* A, int K,
;                                const bf16_t* Bt, int gate_off, float gscale) {
;     ...
;   const float* md = p.mod + ((size_t)l * 3 + modvec_of_tok(row0)) * 6144 + gate_off;
;   EPI_LOOP({
;     float* xp = xrow(p, row0 + rl) + col0 + cl;
;     *xp = *xp + gscale * md[col0 + cl] * acc[mi][ni][j];
;   })
; __global__ void __launch_bounds__(256, 2) fwd_megakernel(Params p_unused) {
;     ...
;         FOR_TILES(128, 8, 8, 8) phase_proj_res(p, l, tm, tn, smem, p.merged, 1024, p.WoT + (size_t)l * DM * DM, 2048, rep == 0 ? 1.f : 0.f);
;         if (l == 0 && rep == 0) { FOR_ITEMS(128) phase_proj_res_ctx(p, l, item, smem, p.merged, 1024, p.WoT + (size_t)l * DM * DM, 2048); } }
.Loutp_erw:
	s_mov_b64 s[44:45], s[26:27]
	global_load_dwordx4 v[64:67], v144, s[44:45] offset:0
	global_load_dwordx4 v[68:71], v144, s[44:45] offset:64
	global_load_dwordx4 v[72:75], v144, s[44:45] offset:128
	global_load_dwordx4 v[76:79], v144, s[44:45] offset:192
	s_add_u32 s44, s44, 0x10000
	s_addc_u32 s45, s45, 0
	global_load_dwordx4 v[80:83], v144, s[44:45] offset:0
	global_load_dwordx4 v[84:87], v144, s[44:45] offset:64
	global_load_dwordx4 v[88:91], v144, s[44:45] offset:128
	global_load_dwordx4 v[92:95], v144, s[44:45] offset:192
	s_add_u32 s44, s44, 0x10000
	s_addc_u32 s45, s45, 0
	global_load_dwordx4 v[96:99], v144, s[44:45] offset:0
	global_load_dwordx4 v[100:103], v144, s[44:45] offset:64
	global_load_dwordx4 v[104:107], v144, s[44:45] offset:128
	global_load_dwordx4 v[108:111], v144, s[44:45] offset:192
	s_add_u32 s44, s44, 0x10000
	s_addc_u32 s45, s45, 0
	global_load_dwordx4 v[112:115], v144, s[44:45] offset:0
	global_load_dwordx4 v[116:119], v144, s[44:45] offset:64
	global_load_dwordx4 v[120:123], v144, s[44:45] offset:128
	global_load_dwordx4 v[124:127], v144, s[44:45] offset:192
	s_waitcnt vmcnt(12)
	v_fmac_f32_e32 v64, v200, v0
	v_fmac_f32_e32 v65, v201, v1
	v_fmac_f32_e32 v66, v202, v2
	v_fmac_f32_e32 v67, v203, v3
	v_fmac_f32_e32 v68, v204, v4
	v_fmac_f32_e32 v69, v205, v5
	v_fmac_f32_e32 v70, v206, v6
	v_fmac_f32_e32 v71, v207, v7
	v_fmac_f32_e32 v72, v208, v8
	v_fmac_f32_e32 v73, v209, v9
	v_fmac_f32_e32 v74, v210, v10
	v_fmac_f32_e32 v75, v211, v11
	v_fmac_f32_e32 v76, v212, v12
	v_fmac_f32_e32 v77, v213, v13
	v_fmac_f32_e32 v78, v214, v14
	v_fmac_f32_e32 v79, v215, v15
	s_waitcnt vmcnt(8)
	v_fmac_f32_e32 v80, v200, v16
	v_fmac_f32_e32 v81, v201, v17
	v_fmac_f32_e32 v82, v202, v18
	v_fmac_f32_e32 v83, v203, v19
	v_fmac_f32_e32 v84, v204, v20
	v_fmac_f32_e32 v85, v205, v21
	v_fmac_f32_e32 v86, v206, v22
	v_fmac_f32_e32 v87, v207, v23
	v_fmac_f32_e32 v88, v208, v24
	v_fmac_f32_e32 v89, v209, v25
	v_fmac_f32_e32 v90, v210, v26
	v_fmac_f32_e32 v91, v211, v27
	v_fmac_f32_e32 v92, v212, v28
	v_fmac_f32_e32 v93, v213, v29
	v_fmac_f32_e32 v94, v214, v30
	v_fmac_f32_e32 v95, v215, v31
	s_waitcnt vmcnt(4)
	v_fmac_f32_e32 v96, v200, v32
	v_fmac_f32_e32 v97, v201, v33
	v_fmac_f32_e32 v98, v202, v34
	v_fmac_f32_e32 v99, v203, v35
	v_fmac_f32_e32 v100, v204, v36
	v_fmac_f32_e32 v101, v205, v37
	v_fmac_f32_e32 v102, v206, v38
	v_fmac_f32_e32 v103, v207, v39
	v_fmac_f32_e32 v104, v208, v40
	v_fmac_f32_e32 v105, v209, v41
	v_fmac_f32_e32 v106, v210, v42
	v_fmac_f32_e32 v107, v211, v43
	v_fmac_f32_e32 v108, v212, v44
	v_fmac_f32_e32 v109, v213, v45
	v_fmac_f32_e32 v110, v214, v46
	v_fmac_f32_e32 v111, v215, v47
	s_waitcnt vmcnt(0)
	v_fmac_f32_e32 v112, v200, v48
	v_fmac_f32_e32 v113, v201, v49
	v_fmac_f32_e32 v114, v202, v50
	v_fmac_f32_e32 v115, v203, v51
	v_fmac_f32_e32 v116, v204, v52
	v_fmac_f32_e32 v117, v205, v53
	v_fmac_f32_e32 v118, v206, v54
	v_fmac_f32_e32 v119, v207, v55
	v_fmac_f32_e32 v120, v208, v56
	v_fmac_f32_e32 v121, v209, v57
	v_fmac_f32_e32 v122, v210, v58
	v_fmac_f32_e32 v123, v211, v59
	v_fmac_f32_e32 v124, v212, v60
	v_fmac_f32_e32 v125, v213, v61
	v_fmac_f32_e32 v126, v214, v62
	v_fmac_f32_e32 v127, v215, v63
	global_store_dwordx4 v144, v[64:67], s[26:27] offset:0
	global_store_dwordx4 v144, v[68:71], s[26:27] offset:64
	global_store_dwordx4 v144, v[72:75], s[26:27] offset:128
	global_store_dwordx4 v144, v[76:79], s[26:27] offset:192
	s_add_u32 s26, s26, 0x10000
	s_addc_u32 s27, s27, 0
	global_store_dwordx4 v144, v[80:83], s[26:27] offset:0
	global_store_dwordx4 v144, v[84:87], s[26:27] offset:64
	global_store_dwordx4 v144, v[88:91], s[26:27] offset:128
	global_store_dwordx4 v144, v[92:95], s[26:27] offset:192
	s_add_u32 s26, s26, 0x10000
	s_addc_u32 s27, s27, 0
	global_store_dwordx4 v144, v[96:99], s[26:27] offset:0
	global_store_dwordx4 v144, v[100:103], s[26:27] offset:64
	global_store_dwordx4 v144, v[104:107], s[26:27] offset:128
	global_store_dwordx4 v144, v[108:111], s[26:27] offset:192
	s_add_u32 s26, s26, 0x10000
	s_addc_u32 s27, s27, 0
	global_store_dwordx4 v144, v[112:115], s[26:27] offset:0
	global_store_dwordx4 v144, v[116:119], s[26:27] offset:64
	global_store_dwordx4 v144, v[120:123], s[26:27] offset:128
	global_store_dwordx4 v144, v[124:127], s[26:27] offset:192
.Loutp_edone:
	v_mov_b32_e32 v0, 0
	v_mov_b32_e32 v1, 0
	v_mov_b32_e32 v2, 0
	v_mov_b32_e32 v3, 0
	v_mov_b32_e32 v4, 0
	v_mov_b32_e32 v5, 0
	v_mov_b32_e32 v6, 0
	v_mov_b32_e32 v7, 0
	v_mov_b32_e32 v8, 0
	v_mov_b32_e32 v9, 0
	v_mov_b32_e32 v10, 0
	v_mov_b32_e32 v11, 0
	v_mov_b32_e32 v12, 0
	v_mov_b32_e32 v13, 0
	v_mov_b32_e32 v14, 0
	v_mov_b32_e32 v15, 0
	v_mov_b32_e32 v16, 0
	v_mov_b32_e32 v17, 0
	v_mov_b32_e32 v18, 0
	v_mov_b32_e32 v19, 0
	v_mov_b32_e32 v20, 0
	v_mov_b32_e32 v21, 0
	v_mov_b32_e32 v22, 0
	v_mov_b32_e32 v23, 0
	v_mov_b32_e32 v24, 0
	v_mov_b32_e32 v25, 0
	v_mov_b32_e32 v26, 0
	v_mov_b32_e32 v27, 0
	v_mov_b32_e32 v28, 0
	v_mov_b32_e32 v29, 0
	v_mov_b32_e32 v30, 0
	v_mov_b32_e32 v31, 0
	v_mov_b32_e32 v32, 0
	v_mov_b32_e32 v33, 0
	v_mov_b32_e32 v34, 0
	v_mov_b32_e32 v35, 0
	v_mov_b32_e32 v36, 0
	v_mov_b32_e32 v37, 0
	v_mov_b32_e32 v38, 0
	v_mov_b32_e32 v39, 0
	v_mov_b32_e32 v40, 0
	v_mov_b32_e32 v41, 0
	v_mov_b32_e32 v42, 0
	v_mov_b32_e32 v43, 0
	v_mov_b32_e32 v44, 0
	v_mov_b32_e32 v45, 0
	v_mov_b32_e32 v46, 0
	v_mov_b32_e32 v47, 0
	v_mov_b32_e32 v48, 0
	v_mov_b32_e32 v49, 0
	v_mov_b32_e32 v50, 0
	v_mov_b32_e32 v51, 0
	v_mov_b32_e32 v52, 0
	v_mov_b32_e32 v53, 0
	v_mov_b32_e32 v54, 0
	v_mov_b32_e32 v55, 0
	v_mov_b32_e32 v56, 0
	v_mov_b32_e32 v57, 0
	v_mov_b32_e32 v58, 0
	v_mov_b32_e32 v59, 0
	v_mov_b32_e32 v60, 0
	v_mov_b32_e32 v61, 0
	v_mov_b32_e32 v62, 0
	v_mov_b32_e32 v63, 0
	s_add_u32 s52, s52, 1
	s_cmp_lt_u32 s4, 128
	s_cselect_b32 s57, 1, 0
	s_cmp_eq_u32 s2, 0
	s_cselect_b32 s57, s57, 0
	s_add_u32 s57, s57, 2
	s_cmp_lt_u32 s52, s57
	s_cbranch_scc1 .Loutp_tile
	s_waitcnt vmcnt(0) lgkmcnt(0)
	s_barrier
	ds_write_b128 v145, v[252:255] offset:40960
	s_waitcnt lgkmcnt(0)
	s_barrier
	s_mov_b64 s[52:53], 0
.LBB0_952:
	v_readlane_b32 s6, v224, 1
	v_readlane_b32 s7, v224, 2
	s_or_b64 s[20:21], s[20:21], s[6:7]
	s_and_b64 vcc, exec, s[20:21]
	s_cbranch_vccnz .LBB0_955
.LBB0_955:
	s_waitcnt vmcnt(0)
	s_barrier
	s_and_saveexec_b64 s[22:23], s[38:39]
	s_cbranch_execz .LBB0_1007
	s_waitcnt vmcnt(0) expcnt(0) lgkmcnt(0)
	ds_read_b32 v2, v145 offset:40960
	ds_read_b32 v0, v145 offset:40964
	s_waitcnt lgkmcnt(1)
	v_cmp_ne_u32_e32 vcc, 0, v2
	s_cbranch_vccnz .LBB0_971
	s_mov_b32 s2, 1
	s_branch .LBB0_959

; __device__ __forceinline__ int otid() { int t = threadIdx.x; asm volatile("" : "+v"(t)); return t; }
; #define FOR_ITEMS(N) for (int item = blockIdx.x; item < (N); item += gridDim.x)
; __device__ void phase_mlp1(CParams& p, int l, int tm, int tn, char* smem) {
;   const int tid = otid();
;   bf16_t* sA = (bf16_t*)smem;
;   bf16_t* sB = sA + 128 * LDSS;
;   int row0 = tm * 128, col0 = tn * 128;
;   f32x4 acc[4][4];
;   zero_acc<4>(acc);
;   gemm_mainloop<4>(p.hbuf + (size_t)row0 * DM, DM, p.W1T + ((size_t)l * DFF + col0) * DM, DM, DM, sA, sB, acc, tid);
; __global__ void __launch_bounds__(256, 2) fwd_megakernel(Params p_unused) {
;     ...
;         if (l == 0) { FOR_ITEMS(128) phase_mlp1(p, l, 128 + (item >> 5), item & 31, smem); } }
.LBB0_1064:
	s_or_b64 exec, exec, s[22:23]
	s_mov_b64 s[22:23], s[34:35]
	s_waitcnt lgkmcnt(0)
	s_barrier
	s_load_dwordx2 s[6:7], s[22:23], 0x120
	s_lshl_b64 s[18:19], s[0:1], 23
	s_load_dwordx2 s[24:25], s[22:23], 0x150
	s_load_dwordx2 s[8:9], s[22:23], 0x1e0
	v_readlane_b32 s16, v224, 4
	v_readlane_b32 s17, v224, 5
	s_waitcnt lgkmcnt(0)
	s_add_u32 s2, s6, s18
	s_addc_u32 s4, s7, s19
	s_add_u32 s42, s2, s16
	s_addc_u32 s43, s4, s17
	v_readlane_b32 s0, v224, 13
	v_readlane_b32 s1, v224, 14
	s_add_u32 s44, s8, s0
	s_addc_u32 s45, s9, s1
	s_add_u32 s2, s6, s16
	s_addc_u32 s4, s7, s17
	s_add_u32 s48, s2, s18
	s_addc_u32 s49, s4, s19
	s_mov_b64 exec, -1
	ds_read_b128 v[252:255], v145 offset:40960
	s_load_dwordx2 s[0:1], s[34:35], 0x150
	s_load_dwordx2 s[6:7], s[34:35], 0x120
	s_load_dwordx2 s[28:29], s[34:35], 0x1e0
	v_readlane_b32 s2, v224, 26
	v_readlane_b32 s4, v225, 4
	v_readfirstlane_b32 s45, v147
	v_and_b32_e32 v166, 63, v147
	s_nop 3
	s_lshr_b32 s45, s45, 6
	s_lshl_b32 s8, s45, 12
	s_cmp_lt_u32 s4, 128
	s_cselect_b32 s92, 1, 0
	s_cmp_eq_u32 s2, 0
	s_cselect_b32 s92, s92, 0
	s_add_u32 s92, s92, 8
	v_lshrrev_b32_e32 v167, 3, v166
	s_lshl_b32 s55, s45, 5
	v_add_u32_e32 v167, s55, v167
	v_and_b32_e32 v226, 7, v166
	v_lshrrev_b32_e32 v227, 4, v166
	s_mov_b32 s51, 0x800
	s_mov_b32 s54, 0x800
	v_xor_b32_e32 v248, v226, v227
	v_xor_b32_e32 v249, 0, v248
	v_lshlrev_b32_e32 v249, 4, v249
	v_add_u32_e32 v250, 0, v167
	v_mul_lo_u32 v236, v250, s51
	v_add_u32_e32 v236, v236, v249
	v_xor_b32_e32 v249, 4, v248
	v_lshlrev_b32_e32 v249, 4, v249
	v_add_u32_e32 v250, 8, v167
	v_mul_lo_u32 v237, v250, s51
	v_add_u32_e32 v237, v237, v249
	v_xor_b32_e32 v249, 0, v248
	v_lshlrev_b32_e32 v249, 4, v249
	v_add_u32_e32 v250, 16, v167
	v_mul_lo_u32 v238, v250, s51
	v_add_u32_e32 v238, v238, v249
	v_xor_b32_e32 v249, 4, v248
	v_lshlrev_b32_e32 v249, 4, v249
	v_add_u32_e32 v250, 24, v167
	v_mul_lo_u32 v239, v250, s51
	v_add_u32_e32 v239, v239, v249
	s_and_b32 s56, s45, 1
	s_lshl_b32 s56, s56, 2
	v_and_b32_e32 v248, 1, v227
	v_or_b32_e32 v248, s56, v248
	v_xor_b32_e32 v248, v226, v248
	v_xor_b32_e32 v249, 0, v248
	v_lshlrev_b32_e32 v249, 4, v249
	v_add_u32_e32 v250, 0, v167
	v_mul_lo_u32 v240, v250, s54
	v_add_u32_e32 v240, v240, v249
	v_xor_b32_e32 v249, 0, v248
	v_lshlrev_b32_e32 v249, 4, v249
	v_add_u32_e32 v250, 8, v167
	v_mul_lo_u32 v241, v250, s54
	v_add_u32_e32 v241, v241, v249
	v_xor_b32_e32 v249, 2, v248
	v_lshlrev_b32_e32 v249, 4, v249
	v_add_u32_e32 v250, 16, v167
	v_mul_lo_u32 v242, v250, s54
	v_add_u32_e32 v242, v242, v249
	v_xor_b32_e32 v249, 2, v248
	v_lshlrev_b32_e32 v249, 4, v249
	v_add_u32_e32 v250, 24, v167
	v_mul_lo_u32 v243, v250, s54
	v_add_u32_e32 v243, v243, v249
	v_and_b32_e32 v167, 15, v166
	v_lshrrev_b32_e32 v227, 4, v166
	s_lshr_b32 s55, s45, 1
	s_and_b32 s56, s45, 1
	s_lshl_b32 s55, s55, 6
	s_lshl_b32 s56, s56, 6
	v_lshrrev_b32_e32 v226, 1, v167
	v_xor_b32_e32 v226, v227, v226
	v_lshlrev_b32_e32 v226, 4, v226
	v_add_u32_e32 v248, s55, v167
	v_lshl_add_u32 v248, v248, 7, v226
	v_xor_b32_e32 v249, 64, v248
	v_lshrrev_b32_e32 v226, 2, v167
	v_lshrrev_b32_e32 v250, 1, v167
	v_and_b32_e32 v250, 1, v250
	v_lshl_or_b32 v250, v226, 1, v250
	v_xor_b32_e32 v250, v227, v250
	v_lshlrev_b32_e32 v250, 4, v250
	v_and_b32_e32 v251, 3, v167
	v_lshl_add_u32 v251, v226, 4, v251
	v_add_u32_e32 v251, s56, v251
	v_lshl_add_u32 v250, v251, 7, v250
	v_xor_b32_e32 v251, 64, v250
	v_lshl_add_u32 v132, v227, 4, s56
	v_lshlrev_b32_e32 v132, 1, v132
	v_add_u32_e32 v144, s55, v167
	s_mov_b32 s51, 0x2000
	v_mul_lo_u32 v144, v144, s51
	v_add_u32_e32 v144, v144, v132
	s_mov_b32 s57, 0x0
	s_mov_b32 s58, 0x4000
	s_mov_b32 s59, 0x8000
	s_mov_b32 s62, 0xc000
	s_mov_b32 s63, 0x10000
	s_waitcnt lgkmcnt(0)
	s_mov_b32 s44, 0
	s_lshr_b32 s51, s44, 1
	s_lshl_b32 s51, s51, 3
	s_and_b32 s54, s4, 7
	s_add_u32 s51, s51, s54
	s_lshr_b32 s54, s51, 1
	s_lshl_b32 s54, s54, 3
	s_lshr_b32 s55, s4, 6
	s_add_u32 s54, s54, s55
	s_lshl_b32 s10, s54, 7
	s_and_b32 s51, s51, 1
	s_lshl_b32 s51, s51, 3
	s_lshr_b32 s55, s4, 3
	s_and_b32 s55, s55, 7
	s_add_u32 s51, s51, s55
	s_lshl_b32 s51, s51, 1
	s_and_b32 s55, s44, 1
	s_add_u32 s51, s51, s55
	s_lshr_b32 s55, s4, 5
	s_add_u32 s55, s55, 128
	s_lshl_b32 s55, s55, 7
	s_and_b32 s54, s4, 31
	s_cmp_ge_u32 s44, 8
	s_cselect_b32 s10, s55, s10
	s_cselect_b32 s51, s54, s51
	s_lshl_b32 s32, s51, 7
	s_mul_i32 s51, s10, 0x800
	s_add_u32 s12, s0, s51
	s_addc_u32 s13, s1, 0
	s_mul_i32 s51, s2, 0x800000
	s_mul_i32 s54, s32, 0x800
	s_add_u32 s51, s51, s54
	s_add_u32 s16, s6, s51
	s_addc_u32 s17, s7, 0
	s_barrier
; __device__ __forceinline__ int otid() { int t = threadIdx.x; asm volatile("" : "+v"(t)); return t; }
; __device__ void phase_mlp1(CParams& p, int l, int tm, int tn, char* smem) {
;   const int tid = otid();
;   bf16_t* sA = (bf16_t*)smem;
;   bf16_t* sB = sA + 128 * LDSS;
;   int row0 = tm * 128, col0 = tn * 128;
;   f32x4 acc[4][4];
;   zero_acc<4>(acc);
;   gemm_mainloop<4>(p.hbuf + (size_t)row0 * DM, DM, p.W1T + ((size_t)l * DFF + col0) * DM, DM, DM, sA, sB, acc, tid);
	s_add_u32 s50, s8, s57
	s_add_u32 m0, s50, 0x0
	s_nop 0
	global_load_lds_dwordx4 v236, s[12:13]
	s_add_u32 m0, s50, 0x400
	s_nop 0
	global_load_lds_dwordx4 v237, s[12:13]
	s_add_u32 m0, s50, 0x800
	s_nop 0
	global_load_lds_dwordx4 v238, s[12:13]
	s_add_u32 m0, s50, 0xc00
	s_nop 0
	global_load_lds_dwordx4 v239, s[12:13]
	s_add_u32 s12, s12, 128
	s_addc_u32 s13, s13, 0
	s_add_u32 s50, s8, s58
	s_add_u32 m0, s50, 0x0
	s_nop 0
	global_load_lds_dwordx4 v240, s[16:17]
	s_add_u32 m0, s50, 0x400
	s_nop 0
	global_load_lds_dwordx4 v241, s[16:17]
	s_add_u32 m0, s50, 0x800
	s_nop 0
	global_load_lds_dwordx4 v242, s[16:17]
	s_add_u32 m0, s50, 0xc00
	s_nop 0
	global_load_lds_dwordx4 v243, s[16:17]
	s_add_u32 s16, s16, 128
	s_addc_u32 s17, s17, 0
	s_add_u32 s50, s8, s59
	s_add_u32 m0, s50, 0x0
	s_nop 0
	global_load_lds_dwordx4 v236, s[12:13]
	s_add_u32 m0, s50, 0x400
	s_nop 0
	global_load_lds_dwordx4 v237, s[12:13]
	s_add_u32 m0, s50, 0x800
	s_nop 0
	global_load_lds_dwordx4 v238, s[12:13]
	s_add_u32 m0, s50, 0xc00
	s_nop 0
	global_load_lds_dwordx4 v239, s[12:13]
	s_add_u32 s12, s12, 128
	s_addc_u32 s13, s13, 0
	s_add_u32 s50, s8, s62
	s_add_u32 m0, s50, 0x0
	s_nop 0
	global_load_lds_dwordx4 v240, s[16:17]
	s_add_u32 m0, s50, 0x400
	s_nop 0
	global_load_lds_dwordx4 v241, s[16:17]
	s_add_u32 m0, s50, 0x800
	s_nop 0
	global_load_lds_dwordx4 v242, s[16:17]
	s_add_u32 m0, s50, 0xc00
	s_nop 0
	global_load_lds_dwordx4 v243, s[16:17]
	s_add_u32 s16, s16, 128
	s_addc_u32 s17, s17, 0
	v_mov_b32_e32 v0, 0
	v_mov_b32_e32 v1, 0
	v_mov_b32_e32 v2, 0
	v_mov_b32_e32 v3, 0
	v_mov_b32_e32 v4, 0
	v_mov_b32_e32 v5, 0
	v_mov_b32_e32 v6, 0
	v_mov_b32_e32 v7, 0
	v_mov_b32_e32 v8, 0
	v_mov_b32_e32 v9, 0
	v_mov_b32_e32 v10, 0
	v_mov_b32_e32 v11, 0
	v_mov_b32_e32 v12, 0
	v_mov_b32_e32 v13, 0
	v_mov_b32_e32 v14, 0
	v_mov_b32_e32 v15, 0
	v_mov_b32_e32 v16, 0
	v_mov_b32_e32 v17, 0
	v_mov_b32_e32 v18, 0
	v_mov_b32_e32 v19, 0
	v_mov_b32_e32 v20, 0
	v_mov_b32_e32 v21, 0
	v_mov_b32_e32 v22, 0
	v_mov_b32_e32 v23, 0
	v_mov_b32_e32 v24, 0
	v_mov_b32_e32 v25, 0
	v_mov_b32_e32 v26, 0
	v_mov_b32_e32 v27, 0
	v_mov_b32_e32 v28, 0
	v_mov_b32_e32 v29, 0
	v_mov_b32_e32 v30, 0
	v_mov_b32_e32 v31, 0
	v_mov_b32_e32 v32, 0
	v_mov_b32_e32 v33, 0
	v_mov_b32_e32 v34, 0
	v_mov_b32_e32 v35, 0
	v_mov_b32_e32 v36, 0
	v_mov_b32_e32 v37, 0
	v_mov_b32_e32 v38, 0
	v_mov_b32_e32 v39, 0
	v_mov_b32_e32 v40, 0
	v_mov_b32_e32 v41, 0
	v_mov_b32_e32 v42, 0
	v_mov_b32_e32 v43, 0
	v_mov_b32_e32 v44, 0
	v_mov_b32_e32 v45, 0
	v_mov_b32_e32 v46, 0
	v_mov_b32_e32 v47, 0
	v_mov_b32_e32 v48, 0
	v_mov_b32_e32 v49, 0
	v_mov_b32_e32 v50, 0
	v_mov_b32_e32 v51, 0
	v_mov_b32_e32 v52, 0
	v_mov_b32_e32 v53, 0
	v_mov_b32_e32 v54, 0
	v_mov_b32_e32 v55, 0
	v_mov_b32_e32 v56, 0
	v_mov_b32_e32 v57, 0
	v_mov_b32_e32 v58, 0
	v_mov_b32_e32 v59, 0
	v_mov_b32_e32 v60, 0
	v_mov_b32_e32 v61, 0
	v_mov_b32_e32 v62, 0
	v_mov_b32_e32 v63, 0
	s_waitcnt vmcnt(8)
	s_barrier
	v_add_u32_e32 v128, s57, v248
	v_add_u32_e32 v130, s58, v250
	ds_read_b128 v[168:171], v128 offset:0
	ds_read_b128 v[184:187], v130 offset:0
	ds_read_b128 v[172:175], v128 offset:2048
	ds_read_b128 v[188:191], v130 offset:512
	ds_read_b128 v[176:179], v128 offset:4096
	ds_read_b128 v[192:195], v130 offset:1024
	ds_read_b128 v[180:183], v128 offset:6144
	ds_read_b128 v[196:199], v130 offset:1536
.Lmlp1_tile:
	s_mul_i32 s51, s10, 0x2000
	s_lshl_b32 s54, s32, 1
	s_add_u32 s51, s51, s54
	s_add_u32 s42, s28, s51
	s_addc_u32 s43, s29, 0
	s_add_u32 s56, s44, 1
	s_sub_u32 s55, s92, 1
	s_min_u32 s56, s56, s55
	s_lshr_b32 s51, s56, 1
	s_lshl_b32 s51, s51, 3
	s_and_b32 s54, s4, 7
	s_add_u32 s51, s51, s54
	s_lshr_b32 s54, s51, 1
	s_lshl_b32 s54, s54, 3
	s_lshr_b32 s55, s4, 6
	s_add_u32 s54, s54, s55
	s_lshl_b32 s10, s54, 7
	s_and_b32 s51, s51, 1
	s_lshl_b32 s51, s51, 3
	s_lshr_b32 s55, s4, 3
	s_and_b32 s55, s55, 7
	s_add_u32 s51, s51, s55
	s_lshl_b32 s51, s51, 1
	s_and_b32 s55, s56, 1
	s_add_u32 s51, s51, s55
	s_lshr_b32 s55, s4, 5
	s_add_u32 s55, s55, 128
	s_lshl_b32 s55, s55, 7
	s_and_b32 s54, s4, 31
	s_cmp_ge_u32 s56, 8
	s_cselect_b32 s10, s55, s10
	s_cselect_b32 s51, s54, s51
	s_lshl_b32 s32, s51, 7
	s_mul_i32 s51, s10, 0x800
	s_add_u32 s24, s0, s51
	s_addc_u32 s25, s1, 0
	s_mul_i32 s51, s2, 0x800000
	s_mul_i32 s54, s32, 0x800
	s_add_u32 s51, s51, s54
	s_add_u32 s26, s6, s51
	s_addc_u32 s27, s7, 0
	s_mov_b32 s45, 0
; template <int NI> ...
;     ...
;   G_LOAD(a0, b0, 0);
;   G_LOAD(a1, b1, 32);
;   __syncthreads();
;   G_WRITE(a0, b0, 0);
;   __syncthreads();
;   for (int kt = 0; kt < nk; kt += 2) {
;     G_LOAD(a0, b0, min((kt + 2) * 32, klast));
;     G_COMPUTE(0);
;     G_WRITE(a1, b1, 1);
;     __syncthreads();
;     G_LOAD(a1, b1, min((kt + 3) * 32, klast));
;     G_COMPUTE(1);
;     G_WRITE(a0, b0, 0);
;     __syncthreads();
; __device__ void phase_mlp1(CParams& p, int l, int tm, int tn, char* smem) {
;     ...
;   EPI_LOOP({
;     float a = fmaxf(acc[mi][ni][j], 0.f);
;     p.hidden[(size_t)(row0 + rl) * DFF + col0 + cl] = f2bf(a * a);
;   })
.Lmlp1_pair:
	s_cmp_eq_u32 s45, 14
	s_cselect_b64 s[12:13], s[24:25], s[12:13]
	s_add_u32 s50, s8, s63
	s_add_u32 m0, s50, 0x0
	s_nop 0
	global_load_lds_dwordx4 v236, s[12:13]
	s_add_u32 m0, s50, 0x400
	s_nop 0
	global_load_lds_dwordx4 v237, s[12:13]
	s_add_u32 m0, s50, 0x800
	s_nop 0
	global_load_lds_dwordx4 v238, s[12:13]
	s_add_u32 m0, s50, 0xc00
	s_nop 0
	global_load_lds_dwordx4 v239, s[12:13]
	s_add_u32 s12, s12, 128
	s_addc_u32 s13, s13, 0
	v_add_u32_e32 v129, s57, v249
	v_add_u32_e32 v131, s58, v251
	s_waitcnt lgkmcnt(0)
	v_mfma_f32_16x16x32_bf16 v[0:3], v[184:187], v[168:171], v[0:3]
	ds_read_b128 v[200:203], v129 offset:0
	v_mfma_f32_16x16x32_bf16 v[4:7], v[188:191], v[168:171], v[4:7]
	ds_read_b128 v[216:219], v131 offset:0
	v_mfma_f32_16x16x32_bf16 v[8:11], v[192:195], v[168:171], v[8:11]
	ds_read_b128 v[204:207], v129 offset:2048
	v_mfma_f32_16x16x32_bf16 v[12:15], v[196:199], v[168:171], v[12:15]
	ds_read_b128 v[220:223], v131 offset:512
	v_mfma_f32_16x16x32_bf16 v[16:19], v[184:187], v[172:175], v[16:19]
	ds_read_b128 v[208:211], v129 offset:4096
	v_mfma_f32_16x16x32_bf16 v[20:23], v[188:191], v[172:175], v[20:23]
	ds_read_b128 v[228:231], v131 offset:1024
	v_mfma_f32_16x16x32_bf16 v[24:27], v[192:195], v[172:175], v[24:27]
	ds_read_b128 v[212:215], v129 offset:6144
	v_mfma_f32_16x16x32_bf16 v[28:31], v[196:199], v[172:175], v[28:31]
	ds_read_b128 v[232:235], v131 offset:1536
	v_mfma_f32_16x16x32_bf16 v[32:35], v[184:187], v[176:179], v[32:35]
	v_mfma_f32_16x16x32_bf16 v[36:39], v[188:191], v[176:179], v[36:39]
	v_mfma_f32_16x16x32_bf16 v[40:43], v[192:195], v[176:179], v[40:43]
	v_mfma_f32_16x16x32_bf16 v[44:47], v[196:199], v[176:179], v[44:47]
	v_mfma_f32_16x16x32_bf16 v[48:51], v[184:187], v[180:183], v[48:51]
	v_mfma_f32_16x16x32_bf16 v[52:55], v[188:191], v[180:183], v[52:55]
	v_mfma_f32_16x16x32_bf16 v[56:59], v[192:195], v[180:183], v[56:59]
	v_mfma_f32_16x16x32_bf16 v[60:63], v[196:199], v[180:183], v[60:63]
	s_waitcnt vmcnt(4) lgkmcnt(0)
	s_barrier
	s_cmp_eq_u32 s45, 14
	s_cselect_b64 s[16:17], s[26:27], s[16:17]
	s_add_u32 s50, s8, s57
	s_add_u32 m0, s50, 0x0
	s_nop 0
	global_load_lds_dwordx4 v240, s[16:17]
	s_add_u32 m0, s50, 0x400
	s_nop 0
	global_load_lds_dwordx4 v241, s[16:17]
	s_add_u32 m0, s50, 0x800
	s_nop 0
	global_load_lds_dwordx4 v242, s[16:17]
	s_add_u32 m0, s50, 0xc00
	s_nop 0
	global_load_lds_dwordx4 v243, s[16:17]
	s_add_u32 s16, s16, 128
	s_addc_u32 s17, s17, 0
	v_add_u32_e32 v128, s59, v248
	v_add_u32_e32 v130, s62, v250
	v_mfma_f32_16x16x32_bf16 v[0:3], v[216:219], v[200:203], v[0:3]
	ds_read_b128 v[168:171], v128 offset:0
	v_mfma_f32_16x16x32_bf16 v[4:7], v[220:223], v[200:203], v[4:7]
	ds_read_b128 v[184:187], v130 offset:0
	v_mfma_f32_16x16x32_bf16 v[8:11], v[228:231], v[200:203], v[8:11]
	ds_read_b128 v[172:175], v128 offset:2048
	v_mfma_f32_16x16x32_bf16 v[12:15], v[232:235], v[200:203], v[12:15]
	ds_read_b128 v[188:191], v130 offset:512
	v_mfma_f32_16x16x32_bf16 v[16:19], v[216:219], v[204:207], v[16:19]
	ds_read_b128 v[176:179], v128 offset:4096
	v_mfma_f32_16x16x32_bf16 v[20:23], v[220:223], v[204:207], v[20:23]
	ds_read_b128 v[192:195], v130 offset:1024
	v_mfma_f32_16x16x32_bf16 v[24:27], v[228:231], v[204:207], v[24:27]
	ds_read_b128 v[180:183], v128 offset:6144
	v_mfma_f32_16x16x32_bf16 v[28:31], v[232:235], v[204:207], v[28:31]
	ds_read_b128 v[196:199], v130 offset:1536
	v_mfma_f32_16x16x32_bf16 v[32:35], v[216:219], v[208:211], v[32:35]
	v_mfma_f32_16x16x32_bf16 v[36:39], v[220:223], v[208:211], v[36:39]
	v_mfma_f32_16x16x32_bf16 v[40:43], v[228:231], v[208:211], v[40:43]
	v_mfma_f32_16x16x32_bf16 v[44:47], v[232:235], v[208:211], v[44:47]
	v_mfma_f32_16x16x32_bf16 v[48:51], v[216:219], v[212:215], v[48:51]
	v_mfma_f32_16x16x32_bf16 v[52:55], v[220:223], v[212:215], v[52:55]
	v_mfma_f32_16x16x32_bf16 v[56:59], v[228:231], v[212:215], v[56:59]
	v_mfma_f32_16x16x32_bf16 v[60:63], v[232:235], v[212:215], v[60:63]
	s_mov_b32 s51, s57
	s_mov_b32 s54, s58
	s_mov_b32 s57, s59
	s_mov_b32 s58, s62
	s_mov_b32 s59, s63
	s_mov_b32 s62, s51
	s_mov_b32 s63, s54
	s_add_u32 s45, s45, 1
	s_cmp_lt_u32 s45, 16
	s_cbranch_scc1 .Lmlp1_pair
	s_nop 15
	s_nop 7
	v_max_f32_e32 v0, 0, v0
	v_max_f32_e32 v1, 0, v1
	v_max_f32_e32 v2, 0, v2
	v_max_f32_e32 v3, 0, v3
	v_max_f32_e32 v4, 0, v4
	v_max_f32_e32 v5, 0, v5
	v_max_f32_e32 v6, 0, v6
	v_max_f32_e32 v7, 0, v7
	v_max_f32_e32 v8, 0, v8
	v_max_f32_e32 v9, 0, v9
	v_max_f32_e32 v10, 0, v10
	v_max_f32_e32 v11, 0, v11
	v_max_f32_e32 v12, 0, v12
	v_max_f32_e32 v13, 0, v13
	v_max_f32_e32 v14, 0, v14
	v_max_f32_e32 v15, 0, v15
	v_mul_f32_e32 v0, v0, v0
	v_mul_f32_e32 v1, v1, v1
	v_mul_f32_e32 v2, v2, v2
	v_mul_f32_e32 v3, v3, v3
	v_mul_f32_e32 v4, v4, v4
	v_mul_f32_e32 v5, v5, v5
	v_mul_f32_e32 v6, v6, v6
	v_mul_f32_e32 v7, v7, v7
	v_mul_f32_e32 v8, v8, v8
	v_mul_f32_e32 v9, v9, v9
	v_mul_f32_e32 v10, v10, v10
	v_mul_f32_e32 v11, v11, v11
	v_mul_f32_e32 v12, v12, v12
	v_mul_f32_e32 v13, v13, v13
	v_mul_f32_e32 v14, v14, v14
	v_mul_f32_e32 v15, v15, v15
	v_cvt_pk_bf16_f32 v64, v0, v1
	v_cvt_pk_bf16_f32 v65, v2, v3
	v_cvt_pk_bf16_f32 v66, v4, v5
	v_cvt_pk_bf16_f32 v67, v6, v7
	global_store_dwordx4 v144, v[64:67], s[42:43] offset:0
	v_cvt_pk_bf16_f32 v68, v8, v9
	v_cvt_pk_bf16_f32 v69, v10, v11
	v_cvt_pk_bf16_f32 v70, v12, v13
	v_cvt_pk_bf16_f32 v71, v14, v15
	global_store_dwordx4 v144, v[68:71], s[42:43] offset:16
	s_add_u32 s42, s42, 0x20000
	s_addc_u32 s43, s43, 0
	v_max_f32_e32 v16, 0, v16
	v_max_f32_e32 v17, 0, v17
	v_max_f32_e32 v18, 0, v18
	v_max_f32_e32 v19, 0, v19
	v_max_f32_e32 v20, 0, v20
	v_max_f32_e32 v21, 0, v21
	v_max_f32_e32 v22, 0, v22
	v_max_f32_e32 v23, 0, v23
; #define FOR_ITEMS(N) for (int item = blockIdx.x; item < (N); item += gridDim.x)
; __device__ void phase_mlp1(CParams& p, int l, int tm, int tn, char* smem) {
;     ...
;   EPI_LOOP({
;     float a = fmaxf(acc[mi][ni][j], 0.f);
;     p.hidden[(size_t)(row0 + rl) * DFF + col0 + cl] = f2bf(a * a);
;   })
; __global__ void __launch_bounds__(256, 2) fwd_megakernel(Params p_unused) {
;     ...
;         if (l == 0) { FOR_ITEMS(128) phase_mlp1(p, l, 128 + (item >> 5), item & 31, smem); } }
	v_max_f32_e32 v24, 0, v24
	v_max_f32_e32 v25, 0, v25
	v_max_f32_e32 v26, 0, v26
	v_max_f32_e32 v27, 0, v27
	v_max_f32_e32 v28, 0, v28
	v_max_f32_e32 v29, 0, v29
	v_max_f32_e32 v30, 0, v30
	v_max_f32_e32 v31, 0, v31
	v_mul_f32_e32 v16, v16, v16
	v_mul_f32_e32 v17, v17, v17
	v_mul_f32_e32 v18, v18, v18
	v_mul_f32_e32 v19, v19, v19
	v_mul_f32_e32 v20, v20, v20
	v_mul_f32_e32 v21, v21, v21
	v_mul_f32_e32 v22, v22, v22
	v_mul_f32_e32 v23, v23, v23
	v_mul_f32_e32 v24, v24, v24
	v_mul_f32_e32 v25, v25, v25
	v_mul_f32_e32 v26, v26, v26
	v_mul_f32_e32 v27, v27, v27
	v_mul_f32_e32 v28, v28, v28
	v_mul_f32_e32 v29, v29, v29
	v_mul_f32_e32 v30, v30, v30
	v_mul_f32_e32 v31, v31, v31
	v_cvt_pk_bf16_f32 v72, v16, v17
	v_cvt_pk_bf16_f32 v73, v18, v19
	v_cvt_pk_bf16_f32 v74, v20, v21
	v_cvt_pk_bf16_f32 v75, v22, v23
	global_store_dwordx4 v144, v[72:75], s[42:43] offset:0
	v_cvt_pk_bf16_f32 v76, v24, v25
	v_cvt_pk_bf16_f32 v77, v26, v27
	v_cvt_pk_bf16_f32 v78, v28, v29
	v_cvt_pk_bf16_f32 v79, v30, v31
	global_store_dwordx4 v144, v[76:79], s[42:43] offset:16
	s_add_u32 s42, s42, 0x20000
	s_addc_u32 s43, s43, 0
	v_max_f32_e32 v32, 0, v32
	v_max_f32_e32 v33, 0, v33
	v_max_f32_e32 v34, 0, v34
	v_max_f32_e32 v35, 0, v35
	v_max_f32_e32 v36, 0, v36
	v_max_f32_e32 v37, 0, v37
	v_max_f32_e32 v38, 0, v38
	v_max_f32_e32 v39, 0, v39
	v_max_f32_e32 v40, 0, v40
	v_max_f32_e32 v41, 0, v41
	v_max_f32_e32 v42, 0, v42
	v_max_f32_e32 v43, 0, v43
	v_max_f32_e32 v44, 0, v44
	v_max_f32_e32 v45, 0, v45
	v_max_f32_e32 v46, 0, v46
	v_max_f32_e32 v47, 0, v47
	v_mul_f32_e32 v32, v32, v32
	v_mul_f32_e32 v33, v33, v33
	v_mul_f32_e32 v34, v34, v34
	v_mul_f32_e32 v35, v35, v35
	v_mul_f32_e32 v36, v36, v36
	v_mul_f32_e32 v37, v37, v37
	v_mul_f32_e32 v38, v38, v38
	v_mul_f32_e32 v39, v39, v39
	v_mul_f32_e32 v40, v40, v40
	v_mul_f32_e32 v41, v41, v41
	v_mul_f32_e32 v42, v42, v42
	v_mul_f32_e32 v43, v43, v43
	v_mul_f32_e32 v44, v44, v44
	v_mul_f32_e32 v45, v45, v45
	v_mul_f32_e32 v46, v46, v46
	v_mul_f32_e32 v47, v47, v47
	v_cvt_pk_bf16_f32 v80, v32, v33
	v_cvt_pk_bf16_f32 v81, v34, v35
	v_cvt_pk_bf16_f32 v82, v36, v37
	v_cvt_pk_bf16_f32 v83, v38, v39
	global_store_dwordx4 v144, v[80:83], s[42:43] offset:0
	v_cvt_pk_bf16_f32 v84, v40, v41
	v_cvt_pk_bf16_f32 v85, v42, v43
	v_cvt_pk_bf16_f32 v86, v44, v45
	v_cvt_pk_bf16_f32 v87, v46, v47
	global_store_dwordx4 v144, v[84:87], s[42:43] offset:16
	s_add_u32 s42, s42, 0x20000
	s_addc_u32 s43, s43, 0
	v_max_f32_e32 v48, 0, v48
	v_max_f32_e32 v49, 0, v49
	v_max_f32_e32 v50, 0, v50
	v_max_f32_e32 v51, 0, v51
	v_max_f32_e32 v52, 0, v52
	v_max_f32_e32 v53, 0, v53
	v_max_f32_e32 v54, 0, v54
	v_max_f32_e32 v55, 0, v55
	v_max_f32_e32 v56, 0, v56
	v_max_f32_e32 v57, 0, v57
	v_max_f32_e32 v58, 0, v58
	v_max_f32_e32 v59, 0, v59
	v_max_f32_e32 v60, 0, v60
	v_max_f32_e32 v61, 0, v61
	v_max_f32_e32 v62, 0, v62
	v_max_f32_e32 v63, 0, v63
	v_mul_f32_e32 v48, v48, v48
	v_mul_f32_e32 v49, v49, v49
	v_mul_f32_e32 v50, v50, v50
	v_mul_f32_e32 v51, v51, v51
	v_mul_f32_e32 v52, v52, v52
	v_mul_f32_e32 v53, v53, v53
	v_mul_f32_e32 v54, v54, v54
	v_mul_f32_e32 v55, v55, v55
	v_mul_f32_e32 v56, v56, v56
	v_mul_f32_e32 v57, v57, v57
	v_mul_f32_e32 v58, v58, v58
	v_mul_f32_e32 v59, v59, v59
	v_mul_f32_e32 v60, v60, v60
	v_mul_f32_e32 v61, v61, v61
	v_mul_f32_e32 v62, v62, v62
	v_mul_f32_e32 v63, v63, v63
	v_cvt_pk_bf16_f32 v88, v48, v49
	v_cvt_pk_bf16_f32 v89, v50, v51
	v_cvt_pk_bf16_f32 v90, v52, v53
	v_cvt_pk_bf16_f32 v91, v54, v55
	global_store_dwordx4 v144, v[88:91], s[42:43] offset:0
	v_cvt_pk_bf16_f32 v92, v56, v57
	v_cvt_pk_bf16_f32 v93, v58, v59
	v_cvt_pk_bf16_f32 v94, v60, v61
	v_cvt_pk_bf16_f32 v95, v62, v63
	global_store_dwordx4 v144, v[92:95], s[42:43] offset:16
	v_mov_b32_e32 v0, 0
	v_mov_b32_e32 v1, 0
	v_mov_b32_e32 v2, 0
	v_mov_b32_e32 v3, 0
	v_mov_b32_e32 v4, 0
	v_mov_b32_e32 v5, 0
	v_mov_b32_e32 v6, 0
	v_mov_b32_e32 v7, 0
	v_mov_b32_e32 v8, 0
	v_mov_b32_e32 v9, 0
	v_mov_b32_e32 v10, 0
	v_mov_b32_e32 v11, 0
	v_mov_b32_e32 v12, 0
	v_mov_b32_e32 v13, 0
	v_mov_b32_e32 v14, 0
	v_mov_b32_e32 v15, 0
	v_mov_b32_e32 v16, 0
	v_mov_b32_e32 v17, 0
	v_mov_b32_e32 v18, 0
	v_mov_b32_e32 v19, 0
	v_mov_b32_e32 v20, 0
	v_mov_b32_e32 v21, 0
	v_mov_b32_e32 v22, 0
	v_mov_b32_e32 v23, 0
	v_mov_b32_e32 v24, 0
	v_mov_b32_e32 v25, 0
	v_mov_b32_e32 v26, 0
	v_mov_b32_e32 v27, 0
	v_mov_b32_e32 v28, 0
	v_mov_b32_e32 v29, 0
	v_mov_b32_e32 v30, 0
	v_mov_b32_e32 v31, 0
	v_mov_b32_e32 v32, 0
	v_mov_b32_e32 v33, 0
	v_mov_b32_e32 v34, 0
	v_mov_b32_e32 v35, 0
	v_mov_b32_e32 v36, 0
	v_mov_b32_e32 v37, 0
	v_mov_b32_e32 v38, 0
	v_mov_b32_e32 v39, 0
	v_mov_b32_e32 v40, 0
	v_mov_b32_e32 v41, 0
	v_mov_b32_e32 v42, 0
	v_mov_b32_e32 v43, 0
	v_mov_b32_e32 v44, 0
	v_mov_b32_e32 v45, 0
	v_mov_b32_e32 v46, 0
	v_mov_b32_e32 v47, 0
	v_mov_b32_e32 v48, 0
	v_mov_b32_e32 v49, 0
	v_mov_b32_e32 v50, 0
	v_mov_b32_e32 v51, 0
	v_mov_b32_e32 v52, 0
	v_mov_b32_e32 v53, 0
	v_mov_b32_e32 v54, 0
	v_mov_b32_e32 v55, 0
	v_mov_b32_e32 v56, 0
	v_mov_b32_e32 v57, 0
	v_mov_b32_e32 v58, 0
	v_mov_b32_e32 v59, 0
	v_mov_b32_e32 v60, 0
	v_mov_b32_e32 v61, 0
	v_mov_b32_e32 v62, 0
	v_mov_b32_e32 v63, 0
	s_add_u32 s44, s44, 1
	s_cmp_lt_u32 s44, s92
	s_cbranch_scc1 .Lmlp1_tile
	s_waitcnt vmcnt(0) lgkmcnt(0)
	s_barrier
	ds_write_b128 v145, v[252:255] offset:40960
	s_waitcnt lgkmcnt(0)
	s_barrier
.LBB0_1070:
	v_cndmask_b32_e64 v0, 0, 1, s[20:21]
	v_readlane_b32 s16, v224, 30
	v_cmp_ne_u32_e64 s[42:43], 1, v0
	s_andn2_b64 vcc, exec, s[20:21]
	s_movk_i32 s1, 0x4000
	v_readlane_b32 s17, v224, 31
	s_cbranch_vccnz .LBB0_1075
.LBB0_1075:
	s_waitcnt vmcnt(0)
	s_waitcnt vmcnt(63) expcnt(7) lgkmcnt(15)
	s_barrier
	s_and_saveexec_b64 s[20:21], s[38:39]
	s_cbranch_execz .LBB0_1127
	s_waitcnt vmcnt(0) expcnt(0) lgkmcnt(0)
	ds_read_b32 v2, v145 offset:40960
	ds_read_b32 v0, v145 offset:40964
	s_waitcnt lgkmcnt(1)
	v_cmp_ne_u32_e32 vcc, 0, v2
	s_cbranch_vccnz .LBB0_1091
	s_mov_b32 s2, 1
	s_branch .LBB0_1079

; __device__ __forceinline__ int otid() { int t = threadIdx.x; asm volatile("" : "+v"(t)); return t; }
; __device__ void phase_proj_res_ctx(CParams& p, int l, int item, char* smem, const bf16_t* A, int K,
;                                    const bf16_t* Bt, int gate_off) {
;   const int tid = otid();
;   bf16_t* sA = (bf16_t*)smem;
;   bf16_t* sB = sA + 128 * LDSS;
;   int ks = item & 3, tn = (item >> 2) & 7, tmc = item >> 5;
;   int row0 = NLAT + tmc * 128, col0 = tn * 128;
;   int kc = K >> 2;
;   f32x4 acc[4][4];
;   zero_acc<4>(acc);
;   gemm_mainloop<4>(A + (size_t)row0 * K + ks * kc, K, Bt + (size_t)col0 * K + ks * kc, K, kc, sA, sB, acc, tid);
.LBB0_1127:
	s_or_b64 exec, exec, s[20:21]
	s_mov_b64 s[20:21], s[34:35]
	s_waitcnt lgkmcnt(0)
	s_barrier
	s_load_dwordx2 s[6:7], s[20:21], 0x128
	s_load_dwordx2 s[22:23], s[20:21], 0x1e0
	s_load_dwordx2 s[24:25], s[20:21], 0x160
	s_load_dwordx2 s[44:45], s[20:21], 0x148
	s_load_dwordx2 s[48:49], s[20:21], 0xf8
	s_waitcnt lgkmcnt(0)
	s_add_u32 s2, s6, s18
	s_addc_u32 s4, s7, s19
	v_readlane_b32 s6, v224, 15
	v_readlane_b32 s7, v224, 16
	s_add_u32 s18, s2, s6
	s_addc_u32 s19, s4, s7
	s_mov_b32 s2, 0
	s_mov_b64 exec, -1
	ds_read_b128 v[252:255], v145 offset:40960
	s_load_dwordx2 s[6:7], s[20:21], 0x1e0
	s_load_dwordx2 s[12:13], s[20:21], 0x128
	s_load_dwordx2 s[28:29], s[20:21], 0xf8
	s_load_dwordx2 s[50:51], s[20:21], 0x160
	v_readlane_b32 s0, v224, 26
	v_readlane_b32 s2, v225, 4
	v_readfirstlane_b32 s54, v147
	v_and_b32_e32 v166, 63, v147
	s_nop 3
	s_lshr_b32 s54, s54, 6
	s_lshl_b32 s4, s54, 12
	v_lshrrev_b32_e32 v167, 3, v166
	s_lshl_b32 s58, s54, 5
	v_add_u32_e32 v167, s58, v167
	v_and_b32_e32 v226, 7, v166
	v_lshrrev_b32_e32 v227, 4, v166
	s_mov_b32 s56, 0x2000
	s_mov_b32 s57, 0x2000
	v_xor_b32_e32 v248, v226, v227
	v_xor_b32_e32 v249, 0, v248
	v_lshlrev_b32_e32 v249, 4, v249
	v_add_u32_e32 v250, 0, v167
	v_mul_lo_u32 v236, v250, s56
	v_add_u32_e32 v236, v236, v249
	v_mul_lo_u32 v240, v250, s57
	v_add_u32_e32 v240, v240, v249
	v_xor_b32_e32 v249, 4, v248
	v_lshlrev_b32_e32 v249, 4, v249
	v_add_u32_e32 v250, 8, v167
	v_mul_lo_u32 v237, v250, s56
	v_add_u32_e32 v237, v237, v249
	v_mul_lo_u32 v241, v250, s57
	v_add_u32_e32 v241, v241, v249
	v_xor_b32_e32 v249, 0, v248
	v_lshlrev_b32_e32 v249, 4, v249
	v_add_u32_e32 v250, 16, v167
	v_mul_lo_u32 v238, v250, s56
	v_add_u32_e32 v238, v238, v249
	v_mul_lo_u32 v242, v250, s57
	v_add_u32_e32 v242, v242, v249
	v_xor_b32_e32 v249, 4, v248
	v_lshlrev_b32_e32 v249, 4, v249
	v_add_u32_e32 v250, 24, v167
	v_mul_lo_u32 v239, v250, s56
	v_add_u32_e32 v239, v239, v249
	v_mul_lo_u32 v243, v250, s57
	v_add_u32_e32 v243, v243, v249
	v_and_b32_e32 v167, 15, v166
	v_lshrrev_b32_e32 v227, 4, v166
	s_lshr_b32 s58, s54, 1
	s_and_b32 s59, s54, 1
	s_lshl_b32 s58, s58, 6
	s_lshl_b32 s59, s59, 6
	v_lshrrev_b32_e32 v226, 1, v167
	v_xor_b32_e32 v226, v227, v226
	v_lshlrev_b32_e32 v226, 4, v226
	v_add_u32_e32 v248, s58, v167
	v_lshl_add_u32 v248, v248, 7, v226
	v_xor_b32_e32 v249, 64, v248
	v_add_u32_e32 v250, s59, v167
	v_lshl_add_u32 v250, v250, 7, v226
	v_xor_b32_e32 v251, 64, v250
	v_lshl_add_u32 v132, v227, 2, s59
	v_lshlrev_b32_e32 v132, 2, v132
	v_add_u32_e32 v144, s58, v167
	v_lshl_add_u32 v144, v144, 12, v132
	s_mov_b32 s62, 0x0
	s_mov_b32 s63, 0x4000
	s_mov_b32 s92, 0x8000
	s_mov_b32 s93, 0xc000
	s_mov_b32 s98, 0x10000
	s_waitcnt lgkmcnt(0)
	s_mov_b32 s32, 0
	s_and_b32 s56, s2, 7
	s_lshl_b32 s56, s56, 4
	s_lshr_b32 s57, s2, 5
	s_add_u32 s56, s56, s57
	s_lshl_b32 s8, s56, 7
	s_lshr_b32 s57, s2, 3
	s_and_b32 s57, s57, 3
	s_lshl_b32 s57, s57, 1
	s_add_u32 s57, s57, s32
	s_lshl_b32 s10, s57, 7
	s_lshr_b32 s56, s2, 5
	s_lshl_b32 s56, s56, 7
	s_add_u32 s56, s56, 0x4000
	s_lshr_b32 s57, s2, 2
	s_and_b32 s57, s57, 7
	s_lshl_b32 s57, s57, 7
	s_and_b32 s58, s2, 3
	s_mul_i32 s58, s58, 0x800
	s_cmp_ge_u32 s32, 2
	s_cselect_b32 s8, s56, s8
	s_cselect_b32 s10, s57, s10
	s_cselect_b32 s58, s58, 0
	s_mul_i32 s56, s8, 0x2000
	s_add_u32 s56, s56, s58
	s_add_u32 s16, s6, s56
	s_addc_u32 s17, s7, 0
	s_mul_i32 s56, s0, 0x800000
	s_mul_i32 s57, s10, 0x2000
	s_add_u32 s56, s56, s57
	s_add_u32 s56, s56, s58
	s_add_u32 s18, s12, s56
	s_addc_u32 s19, s13, 0
	s_barrier
	s_add_u32 s55, s4, s62
	s_add_u32 m0, s55, 0x0
	s_nop 0
	global_load_lds_dwordx4 v236, s[16:17]
	s_add_u32 m0, s55, 0x400
	s_nop 0
	global_load_lds_dwordx4 v237, s[16:17]
	s_add_u32 m0, s55, 0x800
	s_nop 0
	global_load_lds_dwordx4 v238, s[16:17]
	s_add_u32 m0, s55, 0xc00
	s_nop 0
	global_load_lds_dwordx4 v239, s[16:17]
	s_add_u32 s16, s16, 128
	s_addc_u32 s17, s17, 0
	s_add_u32 s55, s4, s63
	s_add_u32 m0, s55, 0x0
	s_nop 0
	global_load_lds_dwordx4 v240, s[18:19]
	s_add_u32 m0, s55, 0x400
	s_nop 0
	global_load_lds_dwordx4 v241, s[18:19]
	s_add_u32 m0, s55, 0x800
	s_nop 0
	global_load_lds_dwordx4 v242, s[18:19]
	s_add_u32 m0, s55, 0xc00
	s_nop 0
	global_load_lds_dwordx4 v243, s[18:19]
	s_add_u32 s18, s18, 128
	s_addc_u32 s19, s19, 0
	s_add_u32 s55, s4, s92
	s_add_u32 m0, s55, 0x0
	s_nop 0
	global_load_lds_dwordx4 v236, s[16:17]
	s_add_u32 m0, s55, 0x400
	s_nop 0
	global_load_lds_dwordx4 v237, s[16:17]
	s_add_u32 m0, s55, 0x800
	s_nop 0
	global_load_lds_dwordx4 v238, s[16:17]
	s_add_u32 m0, s55, 0xc00
	s_nop 0
	global_load_lds_dwordx4 v239, s[16:17]
	s_add_u32 s16, s16, 128
	s_addc_u32 s17, s17, 0
	s_add_u32 s55, s4, s93
	s_add_u32 m0, s55, 0x0
	s_nop 0
	global_load_lds_dwordx4 v240, s[18:19]
	s_add_u32 m0, s55, 0x400
	s_nop 0
	global_load_lds_dwordx4 v241, s[18:19]
	s_add_u32 m0, s55, 0x800
	s_nop 0
	global_load_lds_dwordx4 v242, s[18:19]
	s_add_u32 m0, s55, 0xc00
	s_nop 0
	global_load_lds_dwordx4 v243, s[18:19]
	s_add_u32 s18, s18, 128
	s_addc_u32 s19, s19, 0
	v_mov_b32_e32 v0, 0
	v_mov_b32_e32 v1, 0
	v_mov_b32_e32 v2, 0
	v_mov_b32_e32 v3, 0
	v_mov_b32_e32 v4, 0
	v_mov_b32_e32 v5, 0
	v_mov_b32_e32 v6, 0
	v_mov_b32_e32 v7, 0
	v_mov_b32_e32 v8, 0
	v_mov_b32_e32 v9, 0
	v_mov_b32_e32 v10, 0
	v_mov_b32_e32 v11, 0
	v_mov_b32_e32 v12, 0
	v_mov_b32_e32 v13, 0
	v_mov_b32_e32 v14, 0
	v_mov_b32_e32 v15, 0
	v_mov_b32_e32 v16, 0
	v_mov_b32_e32 v17, 0
	v_mov_b32_e32 v18, 0
	v_mov_b32_e32 v19, 0
	v_mov_b32_e32 v20, 0
	v_mov_b32_e32 v21, 0
	v_mov_b32_e32 v22, 0
	v_mov_b32_e32 v23, 0
	v_mov_b32_e32 v24, 0
	v_mov_b32_e32 v25, 0
	v_mov_b32_e32 v26, 0
	v_mov_b32_e32 v27, 0
	v_mov_b32_e32 v28, 0
	v_mov_b32_e32 v29, 0
	v_mov_b32_e32 v30, 0
	v_mov_b32_e32 v31, 0
	v_mov_b32_e32 v32, 0
	v_mov_b32_e32 v33, 0
	v_mov_b32_e32 v34, 0
	v_mov_b32_e32 v35, 0
	v_mov_b32_e32 v36, 0
	v_mov_b32_e32 v37, 0
	v_mov_b32_e32 v38, 0
	v_mov_b32_e32 v39, 0
	v_mov_b32_e32 v40, 0
	v_mov_b32_e32 v41, 0
	v_mov_b32_e32 v42, 0
	v_mov_b32_e32 v43, 0
	v_mov_b32_e32 v44, 0
	v_mov_b32_e32 v45, 0
	v_mov_b32_e32 v46, 0
	v_mov_b32_e32 v47, 0
	v_mov_b32_e32 v48, 0
	v_mov_b32_e32 v49, 0
	v_mov_b32_e32 v50, 0
	v_mov_b32_e32 v51, 0
	v_mov_b32_e32 v52, 0
	v_mov_b32_e32 v53, 0
	v_mov_b32_e32 v54, 0
	v_mov_b32_e32 v55, 0
	v_mov_b32_e32 v56, 0
	v_mov_b32_e32 v57, 0
	v_mov_b32_e32 v58, 0
	v_mov_b32_e32 v59, 0
	v_mov_b32_e32 v60, 0
	v_mov_b32_e32 v61, 0
	v_mov_b32_e32 v62, 0
	v_mov_b32_e32 v63, 0
	s_waitcnt vmcnt(8)
	s_barrier
	v_add_u32_e32 v128, s62, v248
	v_add_u32_e32 v130, s63, v250
	ds_read_b128 v[168:171], v128 offset:0
	ds_read_b128 v[184:187], v130 offset:0
	ds_read_b128 v[172:175], v128 offset:2048
	ds_read_b128 v[188:191], v130 offset:2048
	ds_read_b128 v[176:179], v128 offset:4096
	ds_read_b128 v[192:195], v130 offset:4096
	ds_read_b128 v[180:183], v128 offset:6144
	ds_read_b128 v[196:199], v130 offset:6144
; __device__ __forceinline__ int otid() { int t = threadIdx.x; asm volatile("" : "+v"(t)); return t; }
; #define FOR_TILES(TM, TN, SR, SC) for (int r_ = 0, nr_ = swz_rounds(TM, TN, SR, SC); r_ < nr_; r_++) if (int tm = 0, tn = 0; swz_tile(r_, TM, TN, SR, SC, tm, tn))
; #define FOR_ITEMS(N) for (int item = blockIdx.x; item < (N); item += gridDim.x)
; #define REPS(k) for (int rep = 0; rep < ((PROBE_DUP == (k)) ? 2 : 1); rep++)
; __device__ void phase_proj_res_ctx(CParams& p, int l, int item, char* smem, const bf16_t* A, int K,
;                                    const bf16_t* Bt, int gate_off) {
;   const int tid = otid();
;   bf16_t* sA = (bf16_t*)smem;
;   bf16_t* sB = sA + 128 * LDSS;
;   int ks = item & 3, tn = (item >> 2) & 7, tmc = item >> 5;
;   int row0 = NLAT + tmc * 128, col0 = tn * 128;
;   int kc = K >> 2;
;   f32x4 acc[4][4];
;   zero_acc<4>(acc);
;   gemm_mainloop<4>(A + (size_t)row0 * K + ks * kc, K, Bt + (size_t)col0 * K + ks * kc, K, kc, sA, sB, acc, tid);
;   const float* md = p.mod + ((size_t)l * 3 + 2) * 6144 + gate_off;
;   float* part = (float*)p.YT1 + (size_t)ks * 512 * DM;
;   EPI_LOOP({ part[(size_t)(row0 - NLAT + rl) * DM + col0 + cl] = md[col0 + cl] * acc[mi][ni][j]; })
; }
; __global__ void __launch_bounds__(256, 2) fwd_megakernel(Params p_unused) {
;     ...
;     REPS(1) {
;       { CParams& p = kparams();
;         FOR_TILES(128, 8, 8, 8) phase_proj_res(p, l, tm, tn, smem, p.hidden, 4096, p.W2T + (size_t)l * DM * DFF, 5120, rep == 0 ? 1.f : 0.f);
;         if (l == 0 && rep == 0) { FOR_ITEMS(128) phase_proj_res_ctx(p, l, item, smem, p.hidden, 4096, p.W2T + (size_t)l * DM * DFF, 5120); } }
;       xcd_barrier(xb);
.Lmlp2_tile:
	s_mul_i32 s56, s0, 3
	s_lshr_b32 s57, s8, 13
	s_add_u32 s56, s56, s57
	s_mul_i32 s56, s56, 6144
	s_add_u32 s56, s56, s10
	s_add_u32 s56, s56, 5120
	s_lshl_b32 s56, s56, 2
	s_add_u32 s52, s50, s56
	s_addc_u32 s53, s51, 0
	s_lshl_b32 s56, s8, 12
	s_lshl_b32 s57, s10, 2
	s_add_u32 s56, s56, s57
	s_add_u32 s40, s28, s56
	s_addc_u32 s41, s29, 0
	s_cmp_ge_u32 s32, 2
	s_cselect_b32 s99, 16, 64
	s_cbranch_scc0 .Lmlp2_xtdone
	s_load_dwordx2 s[40:41], s[20:21], 0x200
	s_sub_u32 s56, s8, 0x4000
	s_lshl_b32 s56, s56, 12
	s_lshl_b32 s57, s10, 2
	s_add_u32 s56, s56, s57
	s_and_b32 s57, s2, 3
	s_lshl_b32 s57, s57, 21
	s_add_u32 s56, s56, s57
	s_waitcnt lgkmcnt(0)
	s_add_u32 s40, s40, s56
	s_addc_u32 s41, s41, 0
.Lmlp2_xtdone:
	s_add_u32 s59, s32, 1
	s_cmp_lt_u32 s2, 128
	s_cselect_b32 s58, 1, 0
	s_cmp_eq_u32 s0, 0
	s_cselect_b32 s58, s58, 0
	s_add_u32 s58, s58, 1
	s_min_u32 s59, s59, s58
	s_and_b32 s56, s2, 7
	s_lshl_b32 s56, s56, 4
	s_lshr_b32 s57, s2, 5
	s_add_u32 s56, s56, s57
	s_lshl_b32 s8, s56, 7
	s_lshr_b32 s57, s2, 3
	s_and_b32 s57, s57, 3
	s_lshl_b32 s57, s57, 1
	s_add_u32 s57, s57, s59
	s_lshl_b32 s10, s57, 7
	s_lshr_b32 s56, s2, 5
	s_lshl_b32 s56, s56, 7
	s_add_u32 s56, s56, 0x4000
	s_lshr_b32 s57, s2, 2
	s_and_b32 s57, s57, 7
	s_lshl_b32 s57, s57, 7
	s_and_b32 s58, s2, 3
	s_mul_i32 s58, s58, 0x800
	s_cmp_ge_u32 s59, 2
	s_cselect_b32 s8, s56, s8
	s_cselect_b32 s10, s57, s10
	s_cselect_b32 s58, s58, 0
	s_mul_i32 s56, s8, 0x2000
	s_add_u32 s56, s56, s58
	s_add_u32 s22, s6, s56
	s_addc_u32 s23, s7, 0
	s_mul_i32 s56, s0, 0x800000
	s_mul_i32 s57, s10, 0x2000
	s_add_u32 s56, s56, s57
	s_add_u32 s56, s56, s58
	s_add_u32 s26, s12, s56
	s_addc_u32 s27, s13, 0
	s_mov_b32 s54, 0
.Lmlp2_pair:
	s_add_u32 s56, s54, 2
	s_cmp_eq_u32 s56, s99
	s_cselect_b64 s[16:17], s[22:23], s[16:17]
	s_add_u32 s55, s4, s98
	s_add_u32 m0, s55, 0x0
	s_nop 0
	global_load_lds_dwordx4 v236, s[16:17]
	s_add_u32 m0, s55, 0x400
	s_nop 0
	global_load_lds_dwordx4 v237, s[16:17]
	s_add_u32 m0, s55, 0x800
	s_nop 0
	global_load_lds_dwordx4 v238, s[16:17]
	s_add_u32 m0, s55, 0xc00
	s_nop 0
	global_load_lds_dwordx4 v239, s[16:17]
	s_add_u32 s16, s16, 128
	s_addc_u32 s17, s17, 0
	v_add_u32_e32 v129, s62, v249
	v_add_u32_e32 v131, s63, v251
	s_waitcnt lgkmcnt(0)
	v_mfma_f32_16x16x32_bf16 v[0:3], v[184:187], v[168:171], v[0:3]
	ds_read_b128 v[200:203], v129 offset:0
	v_mfma_f32_16x16x32_bf16 v[4:7], v[188:191], v[168:171], v[4:7]
	ds_read_b128 v[216:219], v131 offset:0
	v_mfma_f32_16x16x32_bf16 v[8:11], v[192:195], v[168:171], v[8:11]
	ds_read_b128 v[204:207], v129 offset:2048
	v_mfma_f32_16x16x32_bf16 v[12:15], v[196:199], v[168:171], v[12:15]
	ds_read_b128 v[220:223], v131 offset:2048
	v_mfma_f32_16x16x32_bf16 v[16:19], v[184:187], v[172:175], v[16:19]
	ds_read_b128 v[208:211], v129 offset:4096
	v_mfma_f32_16x16x32_bf16 v[20:23], v[188:191], v[172:175], v[20:23]
	ds_read_b128 v[228:231], v131 offset:4096
	v_mfma_f32_16x16x32_bf16 v[24:27], v[192:195], v[172:175], v[24:27]
	ds_read_b128 v[212:215], v129 offset:6144
	v_mfma_f32_16x16x32_bf16 v[28:31], v[196:199], v[172:175], v[28:31]
	ds_read_b128 v[232:235], v131 offset:6144
	v_mfma_f32_16x16x32_bf16 v[32:35], v[184:187], v[176:179], v[32:35]
	v_mfma_f32_16x16x32_bf16 v[36:39], v[188:191], v[176:179], v[36:39]
	v_mfma_f32_16x16x32_bf16 v[40:43], v[192:195], v[176:179], v[40:43]
	v_mfma_f32_16x16x32_bf16 v[44:47], v[196:199], v[176:179], v[44:47]
	v_mfma_f32_16x16x32_bf16 v[48:51], v[184:187], v[180:183], v[48:51]
	v_mfma_f32_16x16x32_bf16 v[52:55], v[188:191], v[180:183], v[52:55]
	v_mfma_f32_16x16x32_bf16 v[56:59], v[192:195], v[180:183], v[56:59]
	v_mfma_f32_16x16x32_bf16 v[60:63], v[196:199], v[180:183], v[60:63]
	s_waitcnt vmcnt(4) lgkmcnt(0)
	s_barrier
	s_add_u32 s56, s54, 2
	s_cmp_eq_u32 s56, s99
	s_cselect_b64 s[18:19], s[26:27], s[18:19]
	s_add_u32 s55, s4, s62
	s_add_u32 m0, s55, 0x0
	s_nop 0
	global_load_lds_dwordx4 v240, s[18:19]
	s_add_u32 m0, s55, 0x400
	s_nop 0
	global_load_lds_dwordx4 v241, s[18:19]
	s_add_u32 m0, s55, 0x800
	s_nop 0
	global_load_lds_dwordx4 v242, s[18:19]
	s_add_u32 m0, s55, 0xc00
	s_nop 0
	global_load_lds_dwordx4 v243, s[18:19]
	s_add_u32 s18, s18, 128
	s_addc_u32 s19, s19, 0
	v_add_u32_e32 v128, s92, v248
	v_add_u32_e32 v130, s93, v250
	v_mfma_f32_16x16x32_bf16 v[0:3], v[216:219], v[200:203], v[0:3]
	ds_read_b128 v[168:171], v128 offset:0
	v_mfma_f32_16x16x32_bf16 v[4:7], v[220:223], v[200:203], v[4:7]
	ds_read_b128 v[184:187], v130 offset:0
	v_mfma_f32_16x16x32_bf16 v[8:11], v[228:231], v[200:203], v[8:11]
	ds_read_b128 v[172:175], v128 offset:2048
	v_mfma_f32_16x16x32_bf16 v[12:15], v[232:235], v[200:203], v[12:15]
	ds_read_b128 v[188:191], v130 offset:2048
	v_mfma_f32_16x16x32_bf16 v[16:19], v[216:219], v[204:207], v[16:19]
	ds_read_b128 v[176:179], v128 offset:4096
	v_mfma_f32_16x16x32_bf16 v[20:23], v[220:223], v[204:207], v[20:23]
	ds_read_b128 v[192:195], v130 offset:4096
	v_mfma_f32_16x16x32_bf16 v[24:27], v[228:231], v[204:207], v[24:27]
	ds_read_b128 v[180:183], v128 offset:6144
	v_mfma_f32_16x16x32_bf16 v[28:31], v[232:235], v[204:207], v[28:31]
	ds_read_b128 v[196:199], v130 offset:6144
	v_mfma_f32_16x16x32_bf16 v[32:35], v[216:219], v[208:211], v[32:35]
	v_mfma_f32_16x16x32_bf16 v[36:39], v[220:223], v[208:211], v[36:39]
	v_mfma_f32_16x16x32_bf16 v[40:43], v[228:231], v[208:211], v[40:43]
	v_mfma_f32_16x16x32_bf16 v[44:47], v[232:235], v[208:211], v[44:47]
	v_mfma_f32_16x16x32_bf16 v[48:51], v[216:219], v[212:215], v[48:51]
	v_mfma_f32_16x16x32_bf16 v[52:55], v[220:223], v[212:215], v[52:55]
	v_mfma_f32_16x16x32_bf16 v[56:59], v[228:231], v[212:215], v[56:59]
	v_mfma_f32_16x16x32_bf16 v[60:63], v[232:235], v[212:215], v[60:63]
	s_mov_b32 s56, s62
	s_mov_b32 s57, s63
	s_mov_b32 s62, s92
	s_mov_b32 s63, s93
	s_mov_b32 s92, s98
	s_mov_b32 s93, s56
	s_mov_b32 s98, s57
	s_add_u32 s54, s54, 1
	s_cmp_lt_u32 s54, s99
	s_cbranch_scc1 .Lmlp2_pair
; __device__ void phase_proj_res_ctx(CParams& p, int l, int item, char* smem, const bf16_t* A, int K,
;                                    const bf16_t* Bt, int gate_off) {
;     ...
;   const float* md = p.mod + ((size_t)l * 3 + 2) * 6144 + gate_off;
;   float* part = (float*)p.YT1 + (size_t)ks * 512 * DM;
;   EPI_LOOP({ part[(size_t)(row0 - NLAT + rl) * DM + col0 + cl] = md[col0 + cl] * acc[mi][ni][j]; })
	s_nop 15
	s_nop 7
	global_load_dwordx4 v[200:203], v132, s[52:53] offset:0
	global_load_dwordx4 v[204:207], v132, s[52:53] offset:64
	global_load_dwordx4 v[208:211], v132, s[52:53] offset:128
	global_load_dwordx4 v[212:215], v132, s[52:53] offset:192
	s_cmp_ge_u32 s32, 2
	s_cbranch_scc0 .Lmlp2_erw
	s_waitcnt vmcnt(0)
	v_mul_f32_e32 v64, v200, v0
	v_mul_f32_e32 v65, v201, v1
	v_mul_f32_e32 v66, v202, v2
	v_mul_f32_e32 v67, v203, v3
	v_mul_f32_e32 v68, v204, v4
	v_mul_f32_e32 v69, v205, v5
	v_mul_f32_e32 v70, v206, v6
	v_mul_f32_e32 v71, v207, v7
	v_mul_f32_e32 v72, v208, v8
	v_mul_f32_e32 v73, v209, v9
	v_mul_f32_e32 v74, v210, v10
	v_mul_f32_e32 v75, v211, v11
	v_mul_f32_e32 v76, v212, v12
	v_mul_f32_e32 v77, v213, v13
	v_mul_f32_e32 v78, v214, v14
	v_mul_f32_e32 v79, v215, v15
	global_store_dwordx4 v144, v[64:67], s[40:41] offset:0
	global_store_dwordx4 v144, v[68:71], s[40:41] offset:64
	global_store_dwordx4 v144, v[72:75], s[40:41] offset:128
	global_store_dwordx4 v144, v[76:79], s[40:41] offset:192
	s_add_u32 s40, s40, 0x10000
	s_addc_u32 s41, s41, 0
	v_mul_f32_e32 v80, v200, v16
	v_mul_f32_e32 v81, v201, v17
	v_mul_f32_e32 v82, v202, v18
	v_mul_f32_e32 v83, v203, v19
	v_mul_f32_e32 v84, v204, v20
	v_mul_f32_e32 v85, v205, v21
	v_mul_f32_e32 v86, v206, v22
	v_mul_f32_e32 v87, v207, v23
	v_mul_f32_e32 v88, v208, v24
	v_mul_f32_e32 v89, v209, v25
	v_mul_f32_e32 v90, v210, v26
	v_mul_f32_e32 v91, v211, v27
	v_mul_f32_e32 v92, v212, v28
	v_mul_f32_e32 v93, v213, v29
	v_mul_f32_e32 v94, v214, v30
	v_mul_f32_e32 v95, v215, v31
	global_store_dwordx4 v144, v[80:83], s[40:41] offset:0
	global_store_dwordx4 v144, v[84:87], s[40:41] offset:64
	global_store_dwordx4 v144, v[88:91], s[40:41] offset:128
	global_store_dwordx4 v144, v[92:95], s[40:41] offset:192
	s_add_u32 s40, s40, 0x10000
	s_addc_u32 s41, s41, 0
	v_mul_f32_e32 v96, v200, v32
	v_mul_f32_e32 v97, v201, v33
	v_mul_f32_e32 v98, v202, v34
	v_mul_f32_e32 v99, v203, v35
	v_mul_f32_e32 v100, v204, v36
	v_mul_f32_e32 v101, v205, v37
	v_mul_f32_e32 v102, v206, v38
	v_mul_f32_e32 v103, v207, v39
	v_mul_f32_e32 v104, v208, v40
	v_mul_f32_e32 v105, v209, v41
	v_mul_f32_e32 v106, v210, v42
	v_mul_f32_e32 v107, v211, v43
	v_mul_f32_e32 v108, v212, v44
	v_mul_f32_e32 v109, v213, v45
	v_mul_f32_e32 v110, v214, v46
	v_mul_f32_e32 v111, v215, v47
	global_store_dwordx4 v144, v[96:99], s[40:41] offset:0
	global_store_dwordx4 v144, v[100:103], s[40:41] offset:64
	global_store_dwordx4 v144, v[104:107], s[40:41] offset:128
	global_store_dwordx4 v144, v[108:111], s[40:41] offset:192
	s_add_u32 s40, s40, 0x10000
	s_addc_u32 s41, s41, 0
	v_mul_f32_e32 v112, v200, v48
	v_mul_f32_e32 v113, v201, v49
	v_mul_f32_e32 v114, v202, v50
	v_mul_f32_e32 v115, v203, v51
	v_mul_f32_e32 v116, v204, v52
	v_mul_f32_e32 v117, v205, v53
	v_mul_f32_e32 v118, v206, v54
	v_mul_f32_e32 v119, v207, v55
	v_mul_f32_e32 v120, v208, v56
	v_mul_f32_e32 v121, v209, v57
	v_mul_f32_e32 v122, v210, v58
	v_mul_f32_e32 v123, v211, v59
	v_mul_f32_e32 v124, v212, v60
	v_mul_f32_e32 v125, v213, v61
	v_mul_f32_e32 v126, v214, v62
	v_mul_f32_e32 v127, v215, v63
	global_store_dwordx4 v144, v[112:115], s[40:41] offset:0
	global_store_dwordx4 v144, v[116:119], s[40:41] offset:64
	global_store_dwordx4 v144, v[120:123], s[40:41] offset:128
	global_store_dwordx4 v144, v[124:127], s[40:41] offset:192
	s_branch .Lmlp2_edone
; #define FOR_TILES(TM, TN, SR, SC) for (int r_ = 0, nr_ = swz_rounds(TM, TN, SR, SC); r_ < nr_; r_++) if (int tm = 0, tn = 0; swz_tile(r_, TM, TN, SR, SC, tm, tn))
; #define FOR_ITEMS(N) for (int item = blockIdx.x; item < (N); item += gridDim.x)
; __device__ void phase_proj_res(CParams& p, int l, int tm, int tn, char* smem, const bf16_t* A, int K,
;                                const bf16_t* Bt, int gate_off, float gscale) {
;     ...
;   const float* md = p.mod + ((size_t)l * 3 + modvec_of_tok(row0)) * 6144 + gate_off;
;   EPI_LOOP({
;     float* xp = xrow(p, row0 + rl) + col0 + cl;
;     *xp = *xp + gscale * md[col0 + cl] * acc[mi][ni][j];
;   })
; __global__ void __launch_bounds__(256, 2) fwd_megakernel(Params p_unused) {
;     ...
;         FOR_TILES(128, 8, 8, 8) phase_proj_res(p, l, tm, tn, smem, p.hidden, 4096, p.W2T + (size_t)l * DM * DFF, 5120, rep == 0 ? 1.f : 0.f);
;         if (l == 0 && rep == 0) { FOR_ITEMS(128) phase_proj_res_ctx(p, l, item, smem, p.hidden, 4096, p.W2T + (size_t)l * DM * DFF, 5120); } }
.Lmlp2_erw:
	s_mov_b64 s[52:53], s[40:41]
	global_load_dwordx4 v[64:67], v144, s[52:53] offset:0
	global_load_dwordx4 v[68:71], v144, s[52:53] offset:64
	global_load_dwordx4 v[72:75], v144, s[52:53] offset:128
	global_load_dwordx4 v[76:79], v144, s[52:53] offset:192
	s_add_u32 s52, s52, 0x10000
	s_addc_u32 s53, s53, 0
	global_load_dwordx4 v[80:83], v144, s[52:53] offset:0
	global_load_dwordx4 v[84:87], v144, s[52:53] offset:64
	global_load_dwordx4 v[88:91], v144, s[52:53] offset:128
	global_load_dwordx4 v[92:95], v144, s[52:53] offset:192
	s_add_u32 s52, s52, 0x10000
	s_addc_u32 s53, s53, 0
	global_load_dwordx4 v[96:99], v144, s[52:53] offset:0
	global_load_dwordx4 v[100:103], v144, s[52:53] offset:64
	global_load_dwordx4 v[104:107], v144, s[52:53] offset:128
	global_load_dwordx4 v[108:111], v144, s[52:53] offset:192
	s_add_u32 s52, s52, 0x10000
	s_addc_u32 s53, s53, 0
	global_load_dwordx4 v[112:115], v144, s[52:53] offset:0
	global_load_dwordx4 v[116:119], v144, s[52:53] offset:64
	global_load_dwordx4 v[120:123], v144, s[52:53] offset:128
	global_load_dwordx4 v[124:127], v144, s[52:53] offset:192
	s_waitcnt vmcnt(12)
	v_fmac_f32_e32 v64, v200, v0
	v_fmac_f32_e32 v65, v201, v1
	v_fmac_f32_e32 v66, v202, v2
	v_fmac_f32_e32 v67, v203, v3
	v_fmac_f32_e32 v68, v204, v4
	v_fmac_f32_e32 v69, v205, v5
	v_fmac_f32_e32 v70, v206, v6
	v_fmac_f32_e32 v71, v207, v7
	v_fmac_f32_e32 v72, v208, v8
	v_fmac_f32_e32 v73, v209, v9
	v_fmac_f32_e32 v74, v210, v10
	v_fmac_f32_e32 v75, v211, v11
	v_fmac_f32_e32 v76, v212, v12
	v_fmac_f32_e32 v77, v213, v13
	v_fmac_f32_e32 v78, v214, v14
	v_fmac_f32_e32 v79, v215, v15
	s_waitcnt vmcnt(8)
	v_fmac_f32_e32 v80, v200, v16
	v_fmac_f32_e32 v81, v201, v17
	v_fmac_f32_e32 v82, v202, v18
	v_fmac_f32_e32 v83, v203, v19
	v_fmac_f32_e32 v84, v204, v20
	v_fmac_f32_e32 v85, v205, v21
	v_fmac_f32_e32 v86, v206, v22
	v_fmac_f32_e32 v87, v207, v23
	v_fmac_f32_e32 v88, v208, v24
	v_fmac_f32_e32 v89, v209, v25
	v_fmac_f32_e32 v90, v210, v26
	v_fmac_f32_e32 v91, v211, v27
	v_fmac_f32_e32 v92, v212, v28
	v_fmac_f32_e32 v93, v213, v29
	v_fmac_f32_e32 v94, v214, v30
	v_fmac_f32_e32 v95, v215, v31
	s_waitcnt vmcnt(4)
	v_fmac_f32_e32 v96, v200, v32
	v_fmac_f32_e32 v97, v201, v33
	v_fmac_f32_e32 v98, v202, v34
	v_fmac_f32_e32 v99, v203, v35
	v_fmac_f32_e32 v100, v204, v36
	v_fmac_f32_e32 v101, v205, v37
	v_fmac_f32_e32 v102, v206, v38
	v_fmac_f32_e32 v103, v207, v39
	v_fmac_f32_e32 v104, v208, v40
	v_fmac_f32_e32 v105, v209, v41
	v_fmac_f32_e32 v106, v210, v42
	v_fmac_f32_e32 v107, v211, v43
	v_fmac_f32_e32 v108, v212, v44
	v_fmac_f32_e32 v109, v213, v45
	v_fmac_f32_e32 v110, v214, v46
	v_fmac_f32_e32 v111, v215, v47
	s_waitcnt vmcnt(0)
	v_fmac_f32_e32 v112, v200, v48
	v_fmac_f32_e32 v113, v201, v49
	v_fmac_f32_e32 v114, v202, v50
	v_fmac_f32_e32 v115, v203, v51
	v_fmac_f32_e32 v116, v204, v52
	v_fmac_f32_e32 v117, v205, v53
	v_fmac_f32_e32 v118, v206, v54
	v_fmac_f32_e32 v119, v207, v55
	v_fmac_f32_e32 v120, v208, v56
	v_fmac_f32_e32 v121, v209, v57
	v_fmac_f32_e32 v122, v210, v58
	v_fmac_f32_e32 v123, v211, v59
	v_fmac_f32_e32 v124, v212, v60
	v_fmac_f32_e32 v125, v213, v61
	v_fmac_f32_e32 v126, v214, v62
	v_fmac_f32_e32 v127, v215, v63
	global_store_dwordx4 v144, v[64:67], s[40:41] offset:0
	global_store_dwordx4 v144, v[68:71], s[40:41] offset:64
	global_store_dwordx4 v144, v[72:75], s[40:41] offset:128
	global_store_dwordx4 v144, v[76:79], s[40:41] offset:192
	s_add_u32 s40, s40, 0x10000
	s_addc_u32 s41, s41, 0
	global_store_dwordx4 v144, v[80:83], s[40:41] offset:0
	global_store_dwordx4 v144, v[84:87], s[40:41] offset:64
	global_store_dwordx4 v144, v[88:91], s[40:41] offset:128
	global_store_dwordx4 v144, v[92:95], s[40:41] offset:192
	s_add_u32 s40, s40, 0x10000
	s_addc_u32 s41, s41, 0
	global_store_dwordx4 v144, v[96:99], s[40:41] offset:0
	global_store_dwordx4 v144, v[100:103], s[40:41] offset:64
	global_store_dwordx4 v144, v[104:107], s[40:41] offset:128
	global_store_dwordx4 v144, v[108:111], s[40:41] offset:192
	s_add_u32 s40, s40, 0x10000
	s_addc_u32 s41, s41, 0
	global_store_dwordx4 v144, v[112:115], s[40:41] offset:0
	global_store_dwordx4 v144, v[116:119], s[40:41] offset:64
	global_store_dwordx4 v144, v[120:123], s[40:41] offset:128
	global_store_dwordx4 v144, v[124:127], s[40:41] offset:192
.Lmlp2_edone:
	v_mov_b32_e32 v0, 0
	v_mov_b32_e32 v1, 0
	v_mov_b32_e32 v2, 0
	v_mov_b32_e32 v3, 0
	v_mov_b32_e32 v4, 0
	v_mov_b32_e32 v5, 0
	v_mov_b32_e32 v6, 0
	v_mov_b32_e32 v7, 0
	v_mov_b32_e32 v8, 0
	v_mov_b32_e32 v9, 0
	v_mov_b32_e32 v10, 0
	v_mov_b32_e32 v11, 0
	v_mov_b32_e32 v12, 0
	v_mov_b32_e32 v13, 0
	v_mov_b32_e32 v14, 0
	v_mov_b32_e32 v15, 0
	v_mov_b32_e32 v16, 0
	v_mov_b32_e32 v17, 0
	v_mov_b32_e32 v18, 0
	v_mov_b32_e32 v19, 0
	v_mov_b32_e32 v20, 0
	v_mov_b32_e32 v21, 0
	v_mov_b32_e32 v22, 0
	v_mov_b32_e32 v23, 0
	v_mov_b32_e32 v24, 0
	v_mov_b32_e32 v25, 0
	v_mov_b32_e32 v26, 0
	v_mov_b32_e32 v27, 0
	v_mov_b32_e32 v28, 0
	v_mov_b32_e32 v29, 0
	v_mov_b32_e32 v30, 0
	v_mov_b32_e32 v31, 0
	v_mov_b32_e32 v32, 0
	v_mov_b32_e32 v33, 0
	v_mov_b32_e32 v34, 0
	v_mov_b32_e32 v35, 0
	v_mov_b32_e32 v36, 0
	v_mov_b32_e32 v37, 0
	v_mov_b32_e32 v38, 0
	v_mov_b32_e32 v39, 0
	v_mov_b32_e32 v40, 0
	v_mov_b32_e32 v41, 0
	v_mov_b32_e32 v42, 0
	v_mov_b32_e32 v43, 0
	v_mov_b32_e32 v44, 0
	v_mov_b32_e32 v45, 0
	v_mov_b32_e32 v46, 0
	v_mov_b32_e32 v47, 0
	v_mov_b32_e32 v48, 0
	v_mov_b32_e32 v49, 0
	v_mov_b32_e32 v50, 0
	v_mov_b32_e32 v51, 0
	v_mov_b32_e32 v52, 0
	v_mov_b32_e32 v53, 0
	v_mov_b32_e32 v54, 0
	v_mov_b32_e32 v55, 0
	v_mov_b32_e32 v56, 0
	v_mov_b32_e32 v57, 0
	v_mov_b32_e32 v58, 0
	v_mov_b32_e32 v59, 0
	v_mov_b32_e32 v60, 0
	v_mov_b32_e32 v61, 0
	v_mov_b32_e32 v62, 0
	v_mov_b32_e32 v63, 0
	s_add_u32 s32, s32, 1
	s_cmp_lt_u32 s2, 128
	s_cselect_b32 s58, 1, 0
	s_cmp_eq_u32 s0, 0
	s_cselect_b32 s58, s58, 0
	s_add_u32 s58, s58, 2
	s_cmp_lt_u32 s32, s58
	s_cbranch_scc1 .Lmlp2_tile
	s_waitcnt vmcnt(0) lgkmcnt(0)
	s_barrier
	ds_write_b128 v145, v[252:255] offset:40960
	s_waitcnt lgkmcnt(0)
	s_barrier
	s_mov_b64 s[50:51], 0
.LBB0_1133:
	s_and_b64 vcc, exec, s[42:43]
	s_cbranch_vccnz .LBB0_1138
.LBB0_1138:
	s_waitcnt vmcnt(0)
	s_barrier
	s_and_saveexec_b64 s[16:17], s[38:39]
	s_cbranch_execnz .LBB0_1139
	s_getpc_b64 s[98:99]
